# LDS address + m0 setup hoisted before each barrier; direct-to-LDS loads issued from the 4th MFMA of each interval
# speedup vs baseline: 1.0891x; 1.0092x over previous
.LBB0_633:
	v_add_u32_e32 v12, s8, v206
	v_add_u32_e32 v13, s8, v10
	v_add_u32_e32 v14, s8, v208
	v_add_u32_e32 v15, s8, v11
	v_readfirstlane_b32 vcc_lo, v6
	s_nop 0
	s_add_u32 vcc_lo, vcc_lo, s9
	s_waitcnt vmcnt(6) lgkmcnt(0)
	s_barrier
	ds_read_b128 v[112:115], v12
	ds_read_b128 v[116:119], v12 offset:2048
	ds_read_b128 v[120:123], v12 offset:4096
	ds_read_b128 v[124:127], v12 offset:6144
	ds_read_b128 v[128:131], v13
	ds_read_b128 v[132:135], v13 offset:2048
	ds_read_b128 v[136:139], v13 offset:4096
	ds_read_b128 v[140:143], v13 offset:6144
	s_mov_b32 m0, vcc_lo
	s_nop 0
	global_load_lds_dwordx4 v0, s[98:99]
	s_add_u32 m0, m0, 0x2000
	s_nop 0
	global_load_lds_dwordx4 v1, s[98:99]
	s_add_u32 m0, m0, 0x2000
	s_nop 0
	global_load_lds_dwordx4 v2, s[98:99]
	s_add_u32 m0, m0, 0x2000
	s_nop 0
	global_load_lds_dwordx4 v3, s[98:99]
	s_add_u32 m0, vcc_lo, 0x8000
	s_nop 0
	global_load_lds_dwordx4 v4, s[100:101]
	s_add_u32 m0, m0, 0x2000
	s_nop 0
	global_load_lds_dwordx4 v5, s[100:101]
	s_add_u32 s98, s98, 0x80
	s_addc_u32 s99, s99, 0
	s_add_u32 s100, s100, 0x80
	s_addc_u32 s101, s101, 0
	s_waitcnt lgkmcnt(0)
	v_mfma_f32_16x16x32_bf16 v[108:111], v[112:115], v[128:131], v[108:111]
	ds_read_b128 v[144:147], v14
	v_mfma_f32_16x16x32_bf16 v[104:107], v[112:115], v[132:135], v[104:107]
	ds_read_b128 v[148:151], v14 offset:2048
	v_mfma_f32_16x16x32_bf16 v[100:103], v[112:115], v[136:139], v[100:103]
	ds_read_b128 v[152:155], v14 offset:4096
	v_mfma_f32_16x16x32_bf16 v[96:99], v[112:115], v[140:143], v[96:99]
	ds_read_b128 v[156:159], v14 offset:6144
	v_mfma_f32_16x16x32_bf16 v[92:95], v[116:119], v[128:131], v[92:95]
	ds_read_b128 v[160:163], v15
	v_mfma_f32_16x16x32_bf16 v[88:91], v[116:119], v[132:135], v[88:91]
	ds_read_b128 v[164:167], v15 offset:2048
	v_mfma_f32_16x16x32_bf16 v[84:87], v[116:119], v[136:139], v[84:87]
	ds_read_b128 v[216:219], v15 offset:4096
	v_mfma_f32_16x16x32_bf16 v[80:83], v[116:119], v[140:143], v[80:83]
	ds_read_b128 v[228:231], v15 offset:6144
	v_mfma_f32_16x16x32_bf16 v[76:79], v[120:123], v[128:131], v[76:79]
	v_mfma_f32_16x16x32_bf16 v[72:75], v[120:123], v[132:135], v[72:75]
	v_mfma_f32_16x16x32_bf16 v[68:71], v[120:123], v[136:139], v[68:71]
	v_mfma_f32_16x16x32_bf16 v[64:67], v[120:123], v[140:143], v[64:67]
	v_mfma_f32_16x16x32_bf16 v[60:63], v[124:127], v[128:131], v[60:63]
	v_mfma_f32_16x16x32_bf16 v[56:59], v[124:127], v[132:135], v[56:59]
	v_mfma_f32_16x16x32_bf16 v[52:55], v[124:127], v[136:139], v[52:55]
	v_mfma_f32_16x16x32_bf16 v[48:51], v[124:127], v[140:143], v[48:51]
	s_mov_b32 s9, s8
	s_add_u32 s8, s8, 0xc000
	s_sub_u32 vcc_lo, s8, 0x24000
	s_cselect_b32 s8, s8, vcc_lo
	s_mov_b32 s47, 1
.Lmyb_steady:
	v_add_u32_e32 v12, s8, v206
	v_add_u32_e32 v13, s8, v10
	v_add_u32_e32 v14, s8, v208
	v_add_u32_e32 v15, s8, v11
	v_readfirstlane_b32 vcc_lo, v6
	s_nop 0
	s_add_u32 vcc_lo, vcc_lo, s9
	s_waitcnt vmcnt(6) lgkmcnt(0)
	s_barrier
	v_mfma_f32_16x16x32_bf16 v[108:111], v[144:147], v[160:163], v[108:111]
	ds_read_b128 v[112:115], v12
	v_mfma_f32_16x16x32_bf16 v[104:107], v[144:147], v[164:167], v[104:107]
	ds_read_b128 v[116:119], v12 offset:2048
	v_mfma_f32_16x16x32_bf16 v[100:103], v[144:147], v[216:219], v[100:103]
	ds_read_b128 v[120:123], v12 offset:4096
	s_mov_b32 m0, vcc_lo
	v_mfma_f32_16x16x32_bf16 v[96:99], v[144:147], v[228:231], v[96:99]
	ds_read_b128 v[124:127], v12 offset:6144
	global_load_lds_dwordx4 v0, s[98:99]
	s_add_u32 m0, m0, 0x2000
	v_mfma_f32_16x16x32_bf16 v[92:95], v[148:151], v[160:163], v[92:95]
	ds_read_b128 v[128:131], v13
	global_load_lds_dwordx4 v1, s[98:99]
	s_add_u32 m0, m0, 0x2000
	v_mfma_f32_16x16x32_bf16 v[88:91], v[148:151], v[164:167], v[88:91]
	ds_read_b128 v[132:135], v13 offset:2048
	global_load_lds_dwordx4 v2, s[98:99]
	s_add_u32 m0, m0, 0x2000
	v_mfma_f32_16x16x32_bf16 v[84:87], v[148:151], v[216:219], v[84:87]
	ds_read_b128 v[136:139], v13 offset:4096
	global_load_lds_dwordx4 v3, s[98:99]
	s_add_u32 m0, vcc_lo, 0x8000
	v_mfma_f32_16x16x32_bf16 v[80:83], v[148:151], v[228:231], v[80:83]
	ds_read_b128 v[140:143], v13 offset:6144
	global_load_lds_dwordx4 v4, s[100:101]
	s_add_u32 m0, m0, 0x2000
	v_mfma_f32_16x16x32_bf16 v[76:79], v[152:155], v[160:163], v[76:79]
	global_load_lds_dwordx4 v5, s[100:101]
	v_mfma_f32_16x16x32_bf16 v[72:75], v[152:155], v[164:167], v[72:75]
	s_add_u32 s98, s98, 0x80
	s_addc_u32 s99, s99, 0
	s_add_u32 s100, s100, 0x80
	s_addc_u32 s101, s101, 0
	v_mfma_f32_16x16x32_bf16 v[68:71], v[152:155], v[216:219], v[68:71]
	v_mfma_f32_16x16x32_bf16 v[64:67], v[152:155], v[228:231], v[64:67]
	v_mfma_f32_16x16x32_bf16 v[60:63], v[156:159], v[160:163], v[60:63]
	v_mfma_f32_16x16x32_bf16 v[56:59], v[156:159], v[164:167], v[56:59]
	v_mfma_f32_16x16x32_bf16 v[52:55], v[156:159], v[216:219], v[52:55]
	v_mfma_f32_16x16x32_bf16 v[48:51], v[156:159], v[228:231], v[48:51]
	s_waitcnt lgkmcnt(0)
	v_mfma_f32_16x16x32_bf16 v[108:111], v[112:115], v[128:131], v[108:111]
	ds_read_b128 v[144:147], v14
	v_mfma_f32_16x16x32_bf16 v[104:107], v[112:115], v[132:135], v[104:107]
	ds_read_b128 v[148:151], v14 offset:2048
	v_mfma_f32_16x16x32_bf16 v[100:103], v[112:115], v[136:139], v[100:103]
	ds_read_b128 v[152:155], v14 offset:4096
	v_mfma_f32_16x16x32_bf16 v[96:99], v[112:115], v[140:143], v[96:99]
	ds_read_b128 v[156:159], v14 offset:6144
	v_mfma_f32_16x16x32_bf16 v[92:95], v[116:119], v[128:131], v[92:95]
	ds_read_b128 v[160:163], v15
	v_mfma_f32_16x16x32_bf16 v[88:91], v[116:119], v[132:135], v[88:91]
	ds_read_b128 v[164:167], v15 offset:2048
	v_mfma_f32_16x16x32_bf16 v[84:87], v[116:119], v[136:139], v[84:87]
	ds_read_b128 v[216:219], v15 offset:4096
	v_mfma_f32_16x16x32_bf16 v[80:83], v[116:119], v[140:143], v[80:83]
	ds_read_b128 v[228:231], v15 offset:6144
	v_mfma_f32_16x16x32_bf16 v[76:79], v[120:123], v[128:131], v[76:79]
	v_mfma_f32_16x16x32_bf16 v[72:75], v[120:123], v[132:135], v[72:75]
	v_mfma_f32_16x16x32_bf16 v[68:71], v[120:123], v[136:139], v[68:71]
	v_mfma_f32_16x16x32_bf16 v[64:67], v[120:123], v[140:143], v[64:67]
	v_mfma_f32_16x16x32_bf16 v[60:63], v[124:127], v[128:131], v[60:63]
	v_mfma_f32_16x16x32_bf16 v[56:59], v[124:127], v[132:135], v[56:59]
	v_mfma_f32_16x16x32_bf16 v[52:55], v[124:127], v[136:139], v[52:55]
	v_mfma_f32_16x16x32_bf16 v[48:51], v[124:127], v[140:143], v[48:51]
	s_mov_b32 s9, s8
	s_add_u32 s8, s8, 0xc000
	s_sub_u32 vcc_lo, s8, 0x24000
	s_cselect_b32 s8, s8, vcc_lo
	s_add_i32 s47, s47, 1
	s_cmp_lt_u32 s47, 14
	s_cbranch_scc1 .Lmyb_steady
	s_andn2_b64 vcc, exec, s[12:13]
	s_cbranch_vccnz .Lmyb_prelast_n
	v_readlane_b32 s98, v250, 0
	v_readlane_b32 s99, v250, 1
	v_readlane_b32 s100, v250, 2
	v_readlane_b32 s101, v250, 3
	v_add_u32_e32 v12, s8, v206
	v_add_u32_e32 v13, s8, v10
	v_add_u32_e32 v14, s8, v208
	v_add_u32_e32 v15, s8, v11
	v_readfirstlane_b32 vcc_lo, v6
	s_nop 0
	s_add_u32 vcc_lo, vcc_lo, s9
	s_waitcnt vmcnt(6) lgkmcnt(0)
	s_barrier
	v_mfma_f32_16x16x32_bf16 v[108:111], v[144:147], v[160:163], v[108:111]
	ds_read_b128 v[112:115], v12
	v_mfma_f32_16x16x32_bf16 v[104:107], v[144:147], v[164:167], v[104:107]
	ds_read_b128 v[116:119], v12 offset:2048
	v_mfma_f32_16x16x32_bf16 v[100:103], v[144:147], v[216:219], v[100:103]
	ds_read_b128 v[120:123], v12 offset:4096
	s_mov_b32 m0, vcc_lo
	v_mfma_f32_16x16x32_bf16 v[96:99], v[144:147], v[228:231], v[96:99]
	ds_read_b128 v[124:127], v12 offset:6144
	global_load_lds_dwordx4 v0, s[98:99]
	s_add_u32 m0, m0, 0x2000
	v_mfma_f32_16x16x32_bf16 v[92:95], v[148:151], v[160:163], v[92:95]
	ds_read_b128 v[128:131], v13
	global_load_lds_dwordx4 v1, s[98:99]
	s_add_u32 m0, m0, 0x2000
	v_mfma_f32_16x16x32_bf16 v[88:91], v[148:151], v[164:167], v[88:91]
	ds_read_b128 v[132:135], v13 offset:2048
	global_load_lds_dwordx4 v2, s[98:99]
	s_add_u32 m0, m0, 0x2000
	v_mfma_f32_16x16x32_bf16 v[84:87], v[148:151], v[216:219], v[84:87]
	ds_read_b128 v[136:139], v13 offset:4096
	global_load_lds_dwordx4 v3, s[98:99]
	s_add_u32 m0, vcc_lo, 0x8000
	v_mfma_f32_16x16x32_bf16 v[80:83], v[148:151], v[228:231], v[80:83]
	ds_read_b128 v[140:143], v13 offset:6144
	global_load_lds_dwordx4 v4, s[100:101]
	s_add_u32 m0, m0, 0x2000
	v_mfma_f32_16x16x32_bf16 v[76:79], v[152:155], v[160:163], v[76:79]
	global_load_lds_dwordx4 v5, s[100:101]
	v_mfma_f32_16x16x32_bf16 v[72:75], v[152:155], v[164:167], v[72:75]
	s_add_u32 s98, s98, 0x80
	s_addc_u32 s99, s99, 0
	s_add_u32 s100, s100, 0x80
	s_addc_u32 s101, s101, 0
	v_mfma_f32_16x16x32_bf16 v[68:71], v[152:155], v[216:219], v[68:71]
	v_mfma_f32_16x16x32_bf16 v[64:67], v[152:155], v[228:231], v[64:67]
	v_mfma_f32_16x16x32_bf16 v[60:63], v[156:159], v[160:163], v[60:63]
	v_mfma_f32_16x16x32_bf16 v[56:59], v[156:159], v[164:167], v[56:59]
	v_mfma_f32_16x16x32_bf16 v[52:55], v[156:159], v[216:219], v[52:55]
	v_mfma_f32_16x16x32_bf16 v[48:51], v[156:159], v[228:231], v[48:51]
	s_waitcnt lgkmcnt(0)
	v_mfma_f32_16x16x32_bf16 v[108:111], v[112:115], v[128:131], v[108:111]
	ds_read_b128 v[144:147], v14
	v_mfma_f32_16x16x32_bf16 v[104:107], v[112:115], v[132:135], v[104:107]
	ds_read_b128 v[148:151], v14 offset:2048
	v_mfma_f32_16x16x32_bf16 v[100:103], v[112:115], v[136:139], v[100:103]
	ds_read_b128 v[152:155], v14 offset:4096
	v_mfma_f32_16x16x32_bf16 v[96:99], v[112:115], v[140:143], v[96:99]
	ds_read_b128 v[156:159], v14 offset:6144
	v_mfma_f32_16x16x32_bf16 v[92:95], v[116:119], v[128:131], v[92:95]
	ds_read_b128 v[160:163], v15
	v_mfma_f32_16x16x32_bf16 v[88:91], v[116:119], v[132:135], v[88:91]
	ds_read_b128 v[164:167], v15 offset:2048
	v_mfma_f32_16x16x32_bf16 v[84:87], v[116:119], v[136:139], v[84:87]
	ds_read_b128 v[216:219], v15 offset:4096
	v_mfma_f32_16x16x32_bf16 v[80:83], v[116:119], v[140:143], v[80:83]
	ds_read_b128 v[228:231], v15 offset:6144
	v_mfma_f32_16x16x32_bf16 v[76:79], v[120:123], v[128:131], v[76:79]
	v_mfma_f32_16x16x32_bf16 v[72:75], v[120:123], v[132:135], v[72:75]
	v_mfma_f32_16x16x32_bf16 v[68:71], v[120:123], v[136:139], v[68:71]
	v_mfma_f32_16x16x32_bf16 v[64:67], v[120:123], v[140:143], v[64:67]
	v_mfma_f32_16x16x32_bf16 v[60:63], v[124:127], v[128:131], v[60:63]
	v_mfma_f32_16x16x32_bf16 v[56:59], v[124:127], v[132:135], v[56:59]
	v_mfma_f32_16x16x32_bf16 v[52:55], v[124:127], v[136:139], v[52:55]
	v_mfma_f32_16x16x32_bf16 v[48:51], v[124:127], v[140:143], v[48:51]
	s_mov_b32 s9, s8
	s_add_u32 s8, s8, 0xc000
	s_sub_u32 vcc_lo, s8, 0x24000
	s_cselect_b32 s8, s8, vcc_lo
	v_add_u32_e32 v12, s8, v206
	v_add_u32_e32 v13, s8, v10
	v_add_u32_e32 v14, s8, v208
	v_add_u32_e32 v15, s8, v11
	v_readfirstlane_b32 vcc_lo, v6
	s_nop 0
	s_add_u32 vcc_lo, vcc_lo, s9
	s_waitcnt vmcnt(6) lgkmcnt(0)
	s_barrier
	v_mfma_f32_16x16x32_bf16 v[108:111], v[144:147], v[160:163], v[108:111]
	ds_read_b128 v[112:115], v12
	v_mfma_f32_16x16x32_bf16 v[104:107], v[144:147], v[164:167], v[104:107]
	ds_read_b128 v[116:119], v12 offset:2048
	v_mfma_f32_16x16x32_bf16 v[100:103], v[144:147], v[216:219], v[100:103]
	ds_read_b128 v[120:123], v12 offset:4096
	s_mov_b32 m0, vcc_lo
	v_mfma_f32_16x16x32_bf16 v[96:99], v[144:147], v[228:231], v[96:99]
	ds_read_b128 v[124:127], v12 offset:6144
	global_load_lds_dwordx4 v0, s[98:99]
	s_add_u32 m0, m0, 0x2000
	v_mfma_f32_16x16x32_bf16 v[92:95], v[148:151], v[160:163], v[92:95]
	ds_read_b128 v[128:131], v13
	global_load_lds_dwordx4 v1, s[98:99]
	s_add_u32 m0, m0, 0x2000
	v_mfma_f32_16x16x32_bf16 v[88:91], v[148:151], v[164:167], v[88:91]
	ds_read_b128 v[132:135], v13 offset:2048
	global_load_lds_dwordx4 v2, s[98:99]
	s_add_u32 m0, m0, 0x2000
	v_mfma_f32_16x16x32_bf16 v[84:87], v[148:151], v[216:219], v[84:87]
	ds_read_b128 v[136:139], v13 offset:4096
	global_load_lds_dwordx4 v3, s[98:99]
	s_add_u32 m0, vcc_lo, 0x8000
	v_mfma_f32_16x16x32_bf16 v[80:83], v[148:151], v[228:231], v[80:83]
	ds_read_b128 v[140:143], v13 offset:6144
	global_load_lds_dwordx4 v4, s[100:101]
	s_add_u32 m0, m0, 0x2000
	v_mfma_f32_16x16x32_bf16 v[76:79], v[152:155], v[160:163], v[76:79]
	global_load_lds_dwordx4 v5, s[100:101]
	v_mfma_f32_16x16x32_bf16 v[72:75], v[152:155], v[164:167], v[72:75]
	s_add_u32 s98, s98, 0x80
	s_addc_u32 s99, s99, 0
	s_add_u32 s100, s100, 0x80
	s_addc_u32 s101, s101, 0
	v_mfma_f32_16x16x32_bf16 v[68:71], v[152:155], v[216:219], v[68:71]
	v_mfma_f32_16x16x32_bf16 v[64:67], v[152:155], v[228:231], v[64:67]
	v_mfma_f32_16x16x32_bf16 v[60:63], v[156:159], v[160:163], v[60:63]
	v_mfma_f32_16x16x32_bf16 v[56:59], v[156:159], v[164:167], v[56:59]
	v_mfma_f32_16x16x32_bf16 v[52:55], v[156:159], v[216:219], v[52:55]
	v_mfma_f32_16x16x32_bf16 v[48:51], v[156:159], v[228:231], v[48:51]
	s_waitcnt lgkmcnt(0)
	v_mfma_f32_16x16x32_bf16 v[108:111], v[112:115], v[128:131], v[108:111]
	ds_read_b128 v[144:147], v14
	v_mfma_f32_16x16x32_bf16 v[104:107], v[112:115], v[132:135], v[104:107]
	ds_read_b128 v[148:151], v14 offset:2048
	v_mfma_f32_16x16x32_bf16 v[100:103], v[112:115], v[136:139], v[100:103]
	ds_read_b128 v[152:155], v14 offset:4096
	v_mfma_f32_16x16x32_bf16 v[96:99], v[112:115], v[140:143], v[96:99]
	ds_read_b128 v[156:159], v14 offset:6144
	v_mfma_f32_16x16x32_bf16 v[92:95], v[116:119], v[128:131], v[92:95]
	ds_read_b128 v[160:163], v15
	v_mfma_f32_16x16x32_bf16 v[88:91], v[116:119], v[132:135], v[88:91]
	ds_read_b128 v[164:167], v15 offset:2048
	v_mfma_f32_16x16x32_bf16 v[84:87], v[116:119], v[136:139], v[84:87]
	ds_read_b128 v[216:219], v15 offset:4096
	v_mfma_f32_16x16x32_bf16 v[80:83], v[116:119], v[140:143], v[80:83]
	ds_read_b128 v[228:231], v15 offset:6144
	v_mfma_f32_16x16x32_bf16 v[76:79], v[120:123], v[128:131], v[76:79]
	v_mfma_f32_16x16x32_bf16 v[72:75], v[120:123], v[132:135], v[72:75]
	v_mfma_f32_16x16x32_bf16 v[68:71], v[120:123], v[136:139], v[68:71]
	v_mfma_f32_16x16x32_bf16 v[64:67], v[120:123], v[140:143], v[64:67]
	v_mfma_f32_16x16x32_bf16 v[60:63], v[124:127], v[128:131], v[60:63]
	v_mfma_f32_16x16x32_bf16 v[56:59], v[124:127], v[132:135], v[56:59]
	v_mfma_f32_16x16x32_bf16 v[52:55], v[124:127], v[136:139], v[52:55]
	v_mfma_f32_16x16x32_bf16 v[48:51], v[124:127], v[140:143], v[48:51]
	s_mov_b32 s9, s8
	s_add_u32 s8, s8, 0xc000
	s_sub_u32 vcc_lo, s8, 0x24000
	s_cselect_b32 s8, s8, vcc_lo
	s_waitcnt lgkmcnt(0)
	v_mfma_f32_16x16x32_bf16 v[108:111], v[144:147], v[160:163], v[108:111]
	v_mfma_f32_16x16x32_bf16 v[104:107], v[144:147], v[164:167], v[104:107]
	v_mfma_f32_16x16x32_bf16 v[100:103], v[144:147], v[216:219], v[100:103]
	v_mfma_f32_16x16x32_bf16 v[96:99], v[144:147], v[228:231], v[96:99]
	v_mfma_f32_16x16x32_bf16 v[92:95], v[148:151], v[160:163], v[92:95]
	v_mfma_f32_16x16x32_bf16 v[88:91], v[148:151], v[164:167], v[88:91]
	v_mfma_f32_16x16x32_bf16 v[84:87], v[148:151], v[216:219], v[84:87]
	v_mfma_f32_16x16x32_bf16 v[80:83], v[148:151], v[228:231], v[80:83]
	v_mfma_f32_16x16x32_bf16 v[76:79], v[152:155], v[160:163], v[76:79]
	v_mfma_f32_16x16x32_bf16 v[72:75], v[152:155], v[164:167], v[72:75]
	v_mfma_f32_16x16x32_bf16 v[68:71], v[152:155], v[216:219], v[68:71]
	v_mfma_f32_16x16x32_bf16 v[64:67], v[152:155], v[228:231], v[64:67]
	v_mfma_f32_16x16x32_bf16 v[60:63], v[156:159], v[160:163], v[60:63]
	v_mfma_f32_16x16x32_bf16 v[56:59], v[156:159], v[164:167], v[56:59]
	v_mfma_f32_16x16x32_bf16 v[52:55], v[156:159], v[216:219], v[52:55]
	v_mfma_f32_16x16x32_bf16 v[48:51], v[156:159], v[228:231], v[48:51]
	s_and_b64 vcc, exec, s[14:15]
	s_nop 7
	s_branch .LBB0_646
.Lmyb_prelast_n:
	v_add_u32_e32 v12, s8, v206
	v_add_u32_e32 v13, s8, v10
	v_add_u32_e32 v14, s8, v208
	v_add_u32_e32 v15, s8, v11
	s_waitcnt vmcnt(6) lgkmcnt(0)
	s_barrier
	v_mfma_f32_16x16x32_bf16 v[108:111], v[144:147], v[160:163], v[108:111]
	ds_read_b128 v[112:115], v12
	v_mfma_f32_16x16x32_bf16 v[104:107], v[144:147], v[164:167], v[104:107]
	ds_read_b128 v[116:119], v12 offset:2048
	v_mfma_f32_16x16x32_bf16 v[100:103], v[144:147], v[216:219], v[100:103]
	ds_read_b128 v[120:123], v12 offset:4096
	v_mfma_f32_16x16x32_bf16 v[96:99], v[144:147], v[228:231], v[96:99]
	ds_read_b128 v[124:127], v12 offset:6144
	v_mfma_f32_16x16x32_bf16 v[92:95], v[148:151], v[160:163], v[92:95]
	ds_read_b128 v[128:131], v13
	v_mfma_f32_16x16x32_bf16 v[88:91], v[148:151], v[164:167], v[88:91]
	ds_read_b128 v[132:135], v13 offset:2048
	v_mfma_f32_16x16x32_bf16 v[84:87], v[148:151], v[216:219], v[84:87]
	ds_read_b128 v[136:139], v13 offset:4096
	v_mfma_f32_16x16x32_bf16 v[80:83], v[148:151], v[228:231], v[80:83]
	ds_read_b128 v[140:143], v13 offset:6144
	v_mfma_f32_16x16x32_bf16 v[76:79], v[152:155], v[160:163], v[76:79]
	v_mfma_f32_16x16x32_bf16 v[72:75], v[152:155], v[164:167], v[72:75]
	v_mfma_f32_16x16x32_bf16 v[68:71], v[152:155], v[216:219], v[68:71]
	v_mfma_f32_16x16x32_bf16 v[64:67], v[152:155], v[228:231], v[64:67]
	v_mfma_f32_16x16x32_bf16 v[60:63], v[156:159], v[160:163], v[60:63]
	v_mfma_f32_16x16x32_bf16 v[56:59], v[156:159], v[164:167], v[56:59]
	v_mfma_f32_16x16x32_bf16 v[52:55], v[156:159], v[216:219], v[52:55]
	v_mfma_f32_16x16x32_bf16 v[48:51], v[156:159], v[228:231], v[48:51]
	s_waitcnt lgkmcnt(0)
	v_mfma_f32_16x16x32_bf16 v[108:111], v[112:115], v[128:131], v[108:111]
	ds_read_b128 v[144:147], v14
	v_mfma_f32_16x16x32_bf16 v[104:107], v[112:115], v[132:135], v[104:107]
	ds_read_b128 v[148:151], v14 offset:2048
	v_mfma_f32_16x16x32_bf16 v[100:103], v[112:115], v[136:139], v[100:103]
	ds_read_b128 v[152:155], v14 offset:4096
	v_mfma_f32_16x16x32_bf16 v[96:99], v[112:115], v[140:143], v[96:99]
	ds_read_b128 v[156:159], v14 offset:6144
	v_mfma_f32_16x16x32_bf16 v[92:95], v[116:119], v[128:131], v[92:95]
	ds_read_b128 v[160:163], v15
	v_mfma_f32_16x16x32_bf16 v[88:91], v[116:119], v[132:135], v[88:91]
	ds_read_b128 v[164:167], v15 offset:2048
	v_mfma_f32_16x16x32_bf16 v[84:87], v[116:119], v[136:139], v[84:87]
	ds_read_b128 v[216:219], v15 offset:4096
	v_mfma_f32_16x16x32_bf16 v[80:83], v[116:119], v[140:143], v[80:83]
	ds_read_b128 v[228:231], v15 offset:6144
	v_mfma_f32_16x16x32_bf16 v[76:79], v[120:123], v[128:131], v[76:79]
	v_mfma_f32_16x16x32_bf16 v[72:75], v[120:123], v[132:135], v[72:75]
	v_mfma_f32_16x16x32_bf16 v[68:71], v[120:123], v[136:139], v[68:71]
	v_mfma_f32_16x16x32_bf16 v[64:67], v[120:123], v[140:143], v[64:67]
	v_mfma_f32_16x16x32_bf16 v[60:63], v[124:127], v[128:131], v[60:63]
	v_mfma_f32_16x16x32_bf16 v[56:59], v[124:127], v[132:135], v[56:59]
	v_mfma_f32_16x16x32_bf16 v[52:55], v[124:127], v[136:139], v[52:55]
	v_mfma_f32_16x16x32_bf16 v[48:51], v[124:127], v[140:143], v[48:51]
	s_mov_b32 s9, s8
	s_add_u32 s8, s8, 0xc000
	s_sub_u32 vcc_lo, s8, 0x24000
	s_cselect_b32 s8, s8, vcc_lo
	v_add_u32_e32 v12, s8, v206
	v_add_u32_e32 v13, s8, v10
	v_add_u32_e32 v14, s8, v208
	v_add_u32_e32 v15, s8, v11
	s_waitcnt vmcnt(0) lgkmcnt(0)
	s_barrier
	v_mfma_f32_16x16x32_bf16 v[108:111], v[144:147], v[160:163], v[108:111]
	ds_read_b128 v[112:115], v12
	v_mfma_f32_16x16x32_bf16 v[104:107], v[144:147], v[164:167], v[104:107]
	ds_read_b128 v[116:119], v12 offset:2048
	v_mfma_f32_16x16x32_bf16 v[100:103], v[144:147], v[216:219], v[100:103]
	ds_read_b128 v[120:123], v12 offset:4096
	v_mfma_f32_16x16x32_bf16 v[96:99], v[144:147], v[228:231], v[96:99]
	ds_read_b128 v[124:127], v12 offset:6144
	v_mfma_f32_16x16x32_bf16 v[92:95], v[148:151], v[160:163], v[92:95]
	ds_read_b128 v[128:131], v13
	v_mfma_f32_16x16x32_bf16 v[88:91], v[148:151], v[164:167], v[88:91]
	ds_read_b128 v[132:135], v13 offset:2048
	v_mfma_f32_16x16x32_bf16 v[84:87], v[148:151], v[216:219], v[84:87]
	ds_read_b128 v[136:139], v13 offset:4096
	v_mfma_f32_16x16x32_bf16 v[80:83], v[148:151], v[228:231], v[80:83]
	ds_read_b128 v[140:143], v13 offset:6144
	v_mfma_f32_16x16x32_bf16 v[76:79], v[152:155], v[160:163], v[76:79]
	v_mfma_f32_16x16x32_bf16 v[72:75], v[152:155], v[164:167], v[72:75]
	v_mfma_f32_16x16x32_bf16 v[68:71], v[152:155], v[216:219], v[68:71]
	v_mfma_f32_16x16x32_bf16 v[64:67], v[152:155], v[228:231], v[64:67]
	v_mfma_f32_16x16x32_bf16 v[60:63], v[156:159], v[160:163], v[60:63]
	v_mfma_f32_16x16x32_bf16 v[56:59], v[156:159], v[164:167], v[56:59]
	v_mfma_f32_16x16x32_bf16 v[52:55], v[156:159], v[216:219], v[52:55]
	v_mfma_f32_16x16x32_bf16 v[48:51], v[156:159], v[228:231], v[48:51]
	s_waitcnt lgkmcnt(0)
	v_mfma_f32_16x16x32_bf16 v[108:111], v[112:115], v[128:131], v[108:111]
	ds_read_b128 v[144:147], v14
	v_mfma_f32_16x16x32_bf16 v[104:107], v[112:115], v[132:135], v[104:107]
	ds_read_b128 v[148:151], v14 offset:2048
	v_mfma_f32_16x16x32_bf16 v[100:103], v[112:115], v[136:139], v[100:103]
	ds_read_b128 v[152:155], v14 offset:4096
	v_mfma_f32_16x16x32_bf16 v[96:99], v[112:115], v[140:143], v[96:99]
	ds_read_b128 v[156:159], v14 offset:6144
	v_mfma_f32_16x16x32_bf16 v[92:95], v[116:119], v[128:131], v[92:95]
	ds_read_b128 v[160:163], v15
	v_mfma_f32_16x16x32_bf16 v[88:91], v[116:119], v[132:135], v[88:91]
	ds_read_b128 v[164:167], v15 offset:2048
	v_mfma_f32_16x16x32_bf16 v[84:87], v[116:119], v[136:139], v[84:87]
	ds_read_b128 v[216:219], v15 offset:4096
	v_mfma_f32_16x16x32_bf16 v[80:83], v[116:119], v[140:143], v[80:83]
	ds_read_b128 v[228:231], v15 offset:6144
	v_mfma_f32_16x16x32_bf16 v[76:79], v[120:123], v[128:131], v[76:79]
	v_mfma_f32_16x16x32_bf16 v[72:75], v[120:123], v[132:135], v[72:75]
	v_mfma_f32_16x16x32_bf16 v[68:71], v[120:123], v[136:139], v[68:71]
	v_mfma_f32_16x16x32_bf16 v[64:67], v[120:123], v[140:143], v[64:67]
	v_mfma_f32_16x16x32_bf16 v[60:63], v[124:127], v[128:131], v[60:63]
	v_mfma_f32_16x16x32_bf16 v[56:59], v[124:127], v[132:135], v[56:59]
	v_mfma_f32_16x16x32_bf16 v[52:55], v[124:127], v[136:139], v[52:55]
	v_mfma_f32_16x16x32_bf16 v[48:51], v[124:127], v[140:143], v[48:51]
	s_mov_b32 s9, s8
	s_add_u32 s8, s8, 0xc000
	s_sub_u32 vcc_lo, s8, 0x24000
	s_cselect_b32 s8, s8, vcc_lo
	s_waitcnt lgkmcnt(0)
	v_mfma_f32_16x16x32_bf16 v[108:111], v[144:147], v[160:163], v[108:111]
	v_mfma_f32_16x16x32_bf16 v[104:107], v[144:147], v[164:167], v[104:107]
	v_mfma_f32_16x16x32_bf16 v[100:103], v[144:147], v[216:219], v[100:103]
	v_mfma_f32_16x16x32_bf16 v[96:99], v[144:147], v[228:231], v[96:99]
	v_mfma_f32_16x16x32_bf16 v[92:95], v[148:151], v[160:163], v[92:95]
	v_mfma_f32_16x16x32_bf16 v[88:91], v[148:151], v[164:167], v[88:91]
	v_mfma_f32_16x16x32_bf16 v[84:87], v[148:151], v[216:219], v[84:87]
	v_mfma_f32_16x16x32_bf16 v[80:83], v[148:151], v[228:231], v[80:83]
	v_mfma_f32_16x16x32_bf16 v[76:79], v[152:155], v[160:163], v[76:79]
	v_mfma_f32_16x16x32_bf16 v[72:75], v[152:155], v[164:167], v[72:75]
	v_mfma_f32_16x16x32_bf16 v[68:71], v[152:155], v[216:219], v[68:71]
	v_mfma_f32_16x16x32_bf16 v[64:67], v[152:155], v[228:231], v[64:67]
	v_mfma_f32_16x16x32_bf16 v[60:63], v[156:159], v[160:163], v[60:63]
	v_mfma_f32_16x16x32_bf16 v[56:59], v[156:159], v[164:167], v[56:59]
	v_mfma_f32_16x16x32_bf16 v[52:55], v[156:159], v[216:219], v[52:55]
	v_mfma_f32_16x16x32_bf16 v[48:51], v[156:159], v[228:231], v[48:51]
	s_and_b64 vcc, exec, s[14:15]
	s_nop 7
	s_branch .LBB0_646

.LBB0_774:
	v_add_u32_e32 v12, s12, v206
	v_add_u32_e32 v13, s12, v10
	v_add_u32_e32 v14, s12, v208
	v_add_u32_e32 v15, s12, v11
	v_readfirstlane_b32 vcc_lo, v6
	s_nop 0
	s_add_u32 vcc_lo, vcc_lo, s13
	s_waitcnt vmcnt(6) lgkmcnt(0)
	s_barrier
	ds_read_b128 v[112:115], v12
	ds_read_b128 v[116:119], v12 offset:2048
	ds_read_b128 v[120:123], v12 offset:4096
	ds_read_b128 v[124:127], v12 offset:6144
	ds_read_b128 v[128:131], v13
	ds_read_b128 v[132:135], v13 offset:2048
	ds_read_b128 v[136:139], v13 offset:4096
	ds_read_b128 v[140:143], v13 offset:6144
	s_mov_b32 m0, vcc_lo
	s_nop 0
	global_load_lds_dwordx4 v0, s[98:99]
	s_add_u32 m0, m0, 0x2000
	s_nop 0
	global_load_lds_dwordx4 v1, s[98:99]
	s_add_u32 m0, m0, 0x2000
	s_nop 0
	global_load_lds_dwordx4 v2, s[98:99]
	s_add_u32 m0, m0, 0x2000
	s_nop 0
	global_load_lds_dwordx4 v3, s[98:99]
	s_add_u32 m0, vcc_lo, 0x8000
	s_nop 0
	global_load_lds_dwordx4 v4, s[100:101]
	s_add_u32 m0, m0, 0x2000
	s_nop 0
	global_load_lds_dwordx4 v5, s[100:101]
	s_add_u32 s98, s98, 0x80
	s_addc_u32 s99, s99, 0
	s_add_u32 s100, s100, 0x80
	s_addc_u32 s101, s101, 0
	s_waitcnt lgkmcnt(0)
	v_mfma_f32_16x16x32_bf16 v[108:111], v[128:131], v[112:115], v[108:111]
	ds_read_b128 v[144:147], v14
	v_mfma_f32_16x16x32_bf16 v[104:107], v[132:135], v[112:115], v[104:107]
	ds_read_b128 v[148:151], v14 offset:2048
	v_mfma_f32_16x16x32_bf16 v[100:103], v[136:139], v[112:115], v[100:103]
	ds_read_b128 v[152:155], v14 offset:4096
	v_mfma_f32_16x16x32_bf16 v[96:99], v[140:143], v[112:115], v[96:99]
	ds_read_b128 v[156:159], v14 offset:6144
	v_mfma_f32_16x16x32_bf16 v[92:95], v[128:131], v[116:119], v[92:95]
	ds_read_b128 v[160:163], v15
	v_mfma_f32_16x16x32_bf16 v[88:91], v[132:135], v[116:119], v[88:91]
	ds_read_b128 v[164:167], v15 offset:2048
	v_mfma_f32_16x16x32_bf16 v[84:87], v[136:139], v[116:119], v[84:87]
	ds_read_b128 v[216:219], v15 offset:4096
	v_mfma_f32_16x16x32_bf16 v[80:83], v[140:143], v[116:119], v[80:83]
	ds_read_b128 v[228:231], v15 offset:6144
	v_mfma_f32_16x16x32_bf16 v[76:79], v[128:131], v[120:123], v[76:79]
	v_mfma_f32_16x16x32_bf16 v[72:75], v[132:135], v[120:123], v[72:75]
	v_mfma_f32_16x16x32_bf16 v[68:71], v[136:139], v[120:123], v[68:71]
	v_mfma_f32_16x16x32_bf16 v[64:67], v[140:143], v[120:123], v[64:67]
	v_mfma_f32_16x16x32_bf16 v[60:63], v[128:131], v[124:127], v[60:63]
	v_mfma_f32_16x16x32_bf16 v[56:59], v[132:135], v[124:127], v[56:59]
	v_mfma_f32_16x16x32_bf16 v[52:55], v[136:139], v[124:127], v[52:55]
	v_mfma_f32_16x16x32_bf16 v[48:51], v[140:143], v[124:127], v[48:51]
	s_mov_b32 s13, s12
	s_add_u32 s12, s12, 0xc000
	s_sub_u32 vcc_lo, s12, 0x24000
	s_cselect_b32 s12, s12, vcc_lo
	s_mov_b32 s38, 1
.Lmyc_steady:
	v_add_u32_e32 v12, s12, v206
	v_add_u32_e32 v13, s12, v10
	v_add_u32_e32 v14, s12, v208
	v_add_u32_e32 v15, s12, v11
	v_readfirstlane_b32 vcc_lo, v6
	s_nop 0
	s_add_u32 vcc_lo, vcc_lo, s13
	s_waitcnt vmcnt(6) lgkmcnt(0)
	s_barrier
	v_mfma_f32_16x16x32_bf16 v[108:111], v[160:163], v[144:147], v[108:111]
	ds_read_b128 v[112:115], v12
	v_mfma_f32_16x16x32_bf16 v[104:107], v[164:167], v[144:147], v[104:107]
	ds_read_b128 v[116:119], v12 offset:2048
	v_mfma_f32_16x16x32_bf16 v[100:103], v[216:219], v[144:147], v[100:103]
	ds_read_b128 v[120:123], v12 offset:4096
	s_mov_b32 m0, vcc_lo
	v_mfma_f32_16x16x32_bf16 v[96:99], v[228:231], v[144:147], v[96:99]
	ds_read_b128 v[124:127], v12 offset:6144
	global_load_lds_dwordx4 v0, s[98:99]
	s_add_u32 m0, m0, 0x2000
	v_mfma_f32_16x16x32_bf16 v[92:95], v[160:163], v[148:151], v[92:95]
	ds_read_b128 v[128:131], v13
	global_load_lds_dwordx4 v1, s[98:99]
	s_add_u32 m0, m0, 0x2000
	v_mfma_f32_16x16x32_bf16 v[88:91], v[164:167], v[148:151], v[88:91]
	ds_read_b128 v[132:135], v13 offset:2048
	global_load_lds_dwordx4 v2, s[98:99]
	s_add_u32 m0, m0, 0x2000
	v_mfma_f32_16x16x32_bf16 v[84:87], v[216:219], v[148:151], v[84:87]
	ds_read_b128 v[136:139], v13 offset:4096
	global_load_lds_dwordx4 v3, s[98:99]
	s_add_u32 m0, vcc_lo, 0x8000
	v_mfma_f32_16x16x32_bf16 v[80:83], v[228:231], v[148:151], v[80:83]
	ds_read_b128 v[140:143], v13 offset:6144
	global_load_lds_dwordx4 v4, s[100:101]
	s_add_u32 m0, m0, 0x2000
	v_mfma_f32_16x16x32_bf16 v[76:79], v[160:163], v[152:155], v[76:79]
	global_load_lds_dwordx4 v5, s[100:101]
	v_mfma_f32_16x16x32_bf16 v[72:75], v[164:167], v[152:155], v[72:75]
	s_add_u32 s98, s98, 0x80
	s_addc_u32 s99, s99, 0
	s_add_u32 s100, s100, 0x80
	s_addc_u32 s101, s101, 0
	v_mfma_f32_16x16x32_bf16 v[68:71], v[216:219], v[152:155], v[68:71]
	v_mfma_f32_16x16x32_bf16 v[64:67], v[228:231], v[152:155], v[64:67]
	v_mfma_f32_16x16x32_bf16 v[60:63], v[160:163], v[156:159], v[60:63]
	v_mfma_f32_16x16x32_bf16 v[56:59], v[164:167], v[156:159], v[56:59]
	v_mfma_f32_16x16x32_bf16 v[52:55], v[216:219], v[156:159], v[52:55]
	v_mfma_f32_16x16x32_bf16 v[48:51], v[228:231], v[156:159], v[48:51]
	s_waitcnt lgkmcnt(0)
	v_mfma_f32_16x16x32_bf16 v[108:111], v[128:131], v[112:115], v[108:111]
	ds_read_b128 v[144:147], v14
	v_mfma_f32_16x16x32_bf16 v[104:107], v[132:135], v[112:115], v[104:107]
	ds_read_b128 v[148:151], v14 offset:2048
	v_mfma_f32_16x16x32_bf16 v[100:103], v[136:139], v[112:115], v[100:103]
	ds_read_b128 v[152:155], v14 offset:4096
	v_mfma_f32_16x16x32_bf16 v[96:99], v[140:143], v[112:115], v[96:99]
	ds_read_b128 v[156:159], v14 offset:6144
	v_mfma_f32_16x16x32_bf16 v[92:95], v[128:131], v[116:119], v[92:95]
	ds_read_b128 v[160:163], v15
	v_mfma_f32_16x16x32_bf16 v[88:91], v[132:135], v[116:119], v[88:91]
	ds_read_b128 v[164:167], v15 offset:2048
	v_mfma_f32_16x16x32_bf16 v[84:87], v[136:139], v[116:119], v[84:87]
	ds_read_b128 v[216:219], v15 offset:4096
	v_mfma_f32_16x16x32_bf16 v[80:83], v[140:143], v[116:119], v[80:83]
	ds_read_b128 v[228:231], v15 offset:6144
	v_mfma_f32_16x16x32_bf16 v[76:79], v[128:131], v[120:123], v[76:79]
	v_mfma_f32_16x16x32_bf16 v[72:75], v[132:135], v[120:123], v[72:75]
	v_mfma_f32_16x16x32_bf16 v[68:71], v[136:139], v[120:123], v[68:71]
	v_mfma_f32_16x16x32_bf16 v[64:67], v[140:143], v[120:123], v[64:67]
	v_mfma_f32_16x16x32_bf16 v[60:63], v[128:131], v[124:127], v[60:63]
	v_mfma_f32_16x16x32_bf16 v[56:59], v[132:135], v[124:127], v[56:59]
	v_mfma_f32_16x16x32_bf16 v[52:55], v[136:139], v[124:127], v[52:55]
	v_mfma_f32_16x16x32_bf16 v[48:51], v[140:143], v[124:127], v[48:51]
	s_mov_b32 s13, s12
	s_add_u32 s12, s12, 0xc000
	s_sub_u32 vcc_lo, s12, 0x24000
	s_cselect_b32 s12, s12, vcc_lo
	s_add_i32 s38, s38, 1
	s_cmp_lt_u32 s38, 14
	s_cbranch_scc1 .Lmyc_steady
	s_andn2_b64 vcc, exec, s[16:17]
	s_cbranch_vccnz .Lmyc_prelast_n
	v_readlane_b32 s98, v250, 0
	v_readlane_b32 s99, v250, 1
	v_readlane_b32 s100, v250, 2
	v_readlane_b32 s101, v250, 3
	v_add_u32_e32 v12, s12, v206
	v_add_u32_e32 v13, s12, v10
	v_add_u32_e32 v14, s12, v208
	v_add_u32_e32 v15, s12, v11
	v_readfirstlane_b32 vcc_lo, v6
	s_nop 0
	s_add_u32 vcc_lo, vcc_lo, s13
	s_waitcnt vmcnt(6) lgkmcnt(0)
	s_barrier
	v_mfma_f32_16x16x32_bf16 v[108:111], v[160:163], v[144:147], v[108:111]
	ds_read_b128 v[112:115], v12
	v_mfma_f32_16x16x32_bf16 v[104:107], v[164:167], v[144:147], v[104:107]
	ds_read_b128 v[116:119], v12 offset:2048
	v_mfma_f32_16x16x32_bf16 v[100:103], v[216:219], v[144:147], v[100:103]
	ds_read_b128 v[120:123], v12 offset:4096
	s_mov_b32 m0, vcc_lo
	v_mfma_f32_16x16x32_bf16 v[96:99], v[228:231], v[144:147], v[96:99]
	ds_read_b128 v[124:127], v12 offset:6144
	global_load_lds_dwordx4 v0, s[98:99]
	s_add_u32 m0, m0, 0x2000
	v_mfma_f32_16x16x32_bf16 v[92:95], v[160:163], v[148:151], v[92:95]
	ds_read_b128 v[128:131], v13
	global_load_lds_dwordx4 v1, s[98:99]
	s_add_u32 m0, m0, 0x2000
	v_mfma_f32_16x16x32_bf16 v[88:91], v[164:167], v[148:151], v[88:91]
	ds_read_b128 v[132:135], v13 offset:2048
	global_load_lds_dwordx4 v2, s[98:99]
	s_add_u32 m0, m0, 0x2000
	v_mfma_f32_16x16x32_bf16 v[84:87], v[216:219], v[148:151], v[84:87]
	ds_read_b128 v[136:139], v13 offset:4096
	global_load_lds_dwordx4 v3, s[98:99]
	s_add_u32 m0, vcc_lo, 0x8000
	v_mfma_f32_16x16x32_bf16 v[80:83], v[228:231], v[148:151], v[80:83]
	ds_read_b128 v[140:143], v13 offset:6144
	global_load_lds_dwordx4 v4, s[100:101]
	s_add_u32 m0, m0, 0x2000
	v_mfma_f32_16x16x32_bf16 v[76:79], v[160:163], v[152:155], v[76:79]
	global_load_lds_dwordx4 v5, s[100:101]
	v_mfma_f32_16x16x32_bf16 v[72:75], v[164:167], v[152:155], v[72:75]
	s_add_u32 s98, s98, 0x80
	s_addc_u32 s99, s99, 0
	s_add_u32 s100, s100, 0x80
	s_addc_u32 s101, s101, 0
	v_mfma_f32_16x16x32_bf16 v[68:71], v[216:219], v[152:155], v[68:71]
	v_mfma_f32_16x16x32_bf16 v[64:67], v[228:231], v[152:155], v[64:67]
	v_mfma_f32_16x16x32_bf16 v[60:63], v[160:163], v[156:159], v[60:63]
	v_mfma_f32_16x16x32_bf16 v[56:59], v[164:167], v[156:159], v[56:59]
	v_mfma_f32_16x16x32_bf16 v[52:55], v[216:219], v[156:159], v[52:55]
	v_mfma_f32_16x16x32_bf16 v[48:51], v[228:231], v[156:159], v[48:51]
	s_waitcnt lgkmcnt(0)
	v_mfma_f32_16x16x32_bf16 v[108:111], v[128:131], v[112:115], v[108:111]
	ds_read_b128 v[144:147], v14
	v_mfma_f32_16x16x32_bf16 v[104:107], v[132:135], v[112:115], v[104:107]
	ds_read_b128 v[148:151], v14 offset:2048
	v_mfma_f32_16x16x32_bf16 v[100:103], v[136:139], v[112:115], v[100:103]
	ds_read_b128 v[152:155], v14 offset:4096
	v_mfma_f32_16x16x32_bf16 v[96:99], v[140:143], v[112:115], v[96:99]
	ds_read_b128 v[156:159], v14 offset:6144
	v_mfma_f32_16x16x32_bf16 v[92:95], v[128:131], v[116:119], v[92:95]
	ds_read_b128 v[160:163], v15
	v_mfma_f32_16x16x32_bf16 v[88:91], v[132:135], v[116:119], v[88:91]
	ds_read_b128 v[164:167], v15 offset:2048
	v_mfma_f32_16x16x32_bf16 v[84:87], v[136:139], v[116:119], v[84:87]
	ds_read_b128 v[216:219], v15 offset:4096
	v_mfma_f32_16x16x32_bf16 v[80:83], v[140:143], v[116:119], v[80:83]
	ds_read_b128 v[228:231], v15 offset:6144
	v_mfma_f32_16x16x32_bf16 v[76:79], v[128:131], v[120:123], v[76:79]
	v_mfma_f32_16x16x32_bf16 v[72:75], v[132:135], v[120:123], v[72:75]
	v_mfma_f32_16x16x32_bf16 v[68:71], v[136:139], v[120:123], v[68:71]
	v_mfma_f32_16x16x32_bf16 v[64:67], v[140:143], v[120:123], v[64:67]
	v_mfma_f32_16x16x32_bf16 v[60:63], v[128:131], v[124:127], v[60:63]
	v_mfma_f32_16x16x32_bf16 v[56:59], v[132:135], v[124:127], v[56:59]
	v_mfma_f32_16x16x32_bf16 v[52:55], v[136:139], v[124:127], v[52:55]
	v_mfma_f32_16x16x32_bf16 v[48:51], v[140:143], v[124:127], v[48:51]
	s_mov_b32 s13, s12
	s_add_u32 s12, s12, 0xc000
	s_sub_u32 vcc_lo, s12, 0x24000
	s_cselect_b32 s12, s12, vcc_lo
	v_add_u32_e32 v12, s12, v206
	v_add_u32_e32 v13, s12, v10
	v_add_u32_e32 v14, s12, v208
	v_add_u32_e32 v15, s12, v11
	v_readfirstlane_b32 vcc_lo, v6
	s_nop 0
	s_add_u32 vcc_lo, vcc_lo, s13
	s_waitcnt vmcnt(6) lgkmcnt(0)
	s_barrier
	v_mfma_f32_16x16x32_bf16 v[108:111], v[160:163], v[144:147], v[108:111]
	ds_read_b128 v[112:115], v12
	v_mfma_f32_16x16x32_bf16 v[104:107], v[164:167], v[144:147], v[104:107]
	ds_read_b128 v[116:119], v12 offset:2048
	v_mfma_f32_16x16x32_bf16 v[100:103], v[216:219], v[144:147], v[100:103]
	ds_read_b128 v[120:123], v12 offset:4096
	s_mov_b32 m0, vcc_lo
	v_mfma_f32_16x16x32_bf16 v[96:99], v[228:231], v[144:147], v[96:99]
	ds_read_b128 v[124:127], v12 offset:6144
	global_load_lds_dwordx4 v0, s[98:99]
	s_add_u32 m0, m0, 0x2000
	v_mfma_f32_16x16x32_bf16 v[92:95], v[160:163], v[148:151], v[92:95]
	ds_read_b128 v[128:131], v13
	global_load_lds_dwordx4 v1, s[98:99]
	s_add_u32 m0, m0, 0x2000
	v_mfma_f32_16x16x32_bf16 v[88:91], v[164:167], v[148:151], v[88:91]
	ds_read_b128 v[132:135], v13 offset:2048
	global_load_lds_dwordx4 v2, s[98:99]
	s_add_u32 m0, m0, 0x2000
	v_mfma_f32_16x16x32_bf16 v[84:87], v[216:219], v[148:151], v[84:87]
	ds_read_b128 v[136:139], v13 offset:4096
	global_load_lds_dwordx4 v3, s[98:99]
	s_add_u32 m0, vcc_lo, 0x8000
	v_mfma_f32_16x16x32_bf16 v[80:83], v[228:231], v[148:151], v[80:83]
	ds_read_b128 v[140:143], v13 offset:6144
	global_load_lds_dwordx4 v4, s[100:101]
	s_add_u32 m0, m0, 0x2000
	v_mfma_f32_16x16x32_bf16 v[76:79], v[160:163], v[152:155], v[76:79]
	global_load_lds_dwordx4 v5, s[100:101]
	v_mfma_f32_16x16x32_bf16 v[72:75], v[164:167], v[152:155], v[72:75]
	s_add_u32 s98, s98, 0x80
	s_addc_u32 s99, s99, 0
	s_add_u32 s100, s100, 0x80
	s_addc_u32 s101, s101, 0
	v_mfma_f32_16x16x32_bf16 v[68:71], v[216:219], v[152:155], v[68:71]
	v_mfma_f32_16x16x32_bf16 v[64:67], v[228:231], v[152:155], v[64:67]
	v_mfma_f32_16x16x32_bf16 v[60:63], v[160:163], v[156:159], v[60:63]
	v_mfma_f32_16x16x32_bf16 v[56:59], v[164:167], v[156:159], v[56:59]
	v_mfma_f32_16x16x32_bf16 v[52:55], v[216:219], v[156:159], v[52:55]
	v_mfma_f32_16x16x32_bf16 v[48:51], v[228:231], v[156:159], v[48:51]
	s_waitcnt lgkmcnt(0)
	v_mfma_f32_16x16x32_bf16 v[108:111], v[128:131], v[112:115], v[108:111]
	ds_read_b128 v[144:147], v14
	v_mfma_f32_16x16x32_bf16 v[104:107], v[132:135], v[112:115], v[104:107]
	ds_read_b128 v[148:151], v14 offset:2048
	v_mfma_f32_16x16x32_bf16 v[100:103], v[136:139], v[112:115], v[100:103]
	ds_read_b128 v[152:155], v14 offset:4096
	v_mfma_f32_16x16x32_bf16 v[96:99], v[140:143], v[112:115], v[96:99]
	ds_read_b128 v[156:159], v14 offset:6144
	v_mfma_f32_16x16x32_bf16 v[92:95], v[128:131], v[116:119], v[92:95]
	ds_read_b128 v[160:163], v15
	v_mfma_f32_16x16x32_bf16 v[88:91], v[132:135], v[116:119], v[88:91]
	ds_read_b128 v[164:167], v15 offset:2048
	v_mfma_f32_16x16x32_bf16 v[84:87], v[136:139], v[116:119], v[84:87]
	ds_read_b128 v[216:219], v15 offset:4096
	v_mfma_f32_16x16x32_bf16 v[80:83], v[140:143], v[116:119], v[80:83]
	ds_read_b128 v[228:231], v15 offset:6144
	v_mfma_f32_16x16x32_bf16 v[76:79], v[128:131], v[120:123], v[76:79]
	v_mfma_f32_16x16x32_bf16 v[72:75], v[132:135], v[120:123], v[72:75]
	v_mfma_f32_16x16x32_bf16 v[68:71], v[136:139], v[120:123], v[68:71]
	v_mfma_f32_16x16x32_bf16 v[64:67], v[140:143], v[120:123], v[64:67]
	v_mfma_f32_16x16x32_bf16 v[60:63], v[128:131], v[124:127], v[60:63]
	v_mfma_f32_16x16x32_bf16 v[56:59], v[132:135], v[124:127], v[56:59]
	v_mfma_f32_16x16x32_bf16 v[52:55], v[136:139], v[124:127], v[52:55]
	v_mfma_f32_16x16x32_bf16 v[48:51], v[140:143], v[124:127], v[48:51]
	s_mov_b32 s13, s12
	s_add_u32 s12, s12, 0xc000
	s_sub_u32 vcc_lo, s12, 0x24000
	s_cselect_b32 s12, s12, vcc_lo
	s_waitcnt lgkmcnt(0)
	v_mfma_f32_16x16x32_bf16 v[108:111], v[160:163], v[144:147], v[108:111]
	v_mfma_f32_16x16x32_bf16 v[104:107], v[164:167], v[144:147], v[104:107]
	v_mfma_f32_16x16x32_bf16 v[100:103], v[216:219], v[144:147], v[100:103]
	v_mfma_f32_16x16x32_bf16 v[96:99], v[228:231], v[144:147], v[96:99]
	v_mfma_f32_16x16x32_bf16 v[92:95], v[160:163], v[148:151], v[92:95]
	v_mfma_f32_16x16x32_bf16 v[88:91], v[164:167], v[148:151], v[88:91]
	v_mfma_f32_16x16x32_bf16 v[84:87], v[216:219], v[148:151], v[84:87]
	v_mfma_f32_16x16x32_bf16 v[80:83], v[228:231], v[148:151], v[80:83]
	v_mfma_f32_16x16x32_bf16 v[76:79], v[160:163], v[152:155], v[76:79]
	v_mfma_f32_16x16x32_bf16 v[72:75], v[164:167], v[152:155], v[72:75]
	v_mfma_f32_16x16x32_bf16 v[68:71], v[216:219], v[152:155], v[68:71]
	v_mfma_f32_16x16x32_bf16 v[64:67], v[228:231], v[152:155], v[64:67]
	v_mfma_f32_16x16x32_bf16 v[60:63], v[160:163], v[156:159], v[60:63]
	v_mfma_f32_16x16x32_bf16 v[56:59], v[164:167], v[156:159], v[56:59]
	v_mfma_f32_16x16x32_bf16 v[52:55], v[216:219], v[156:159], v[52:55]
	v_mfma_f32_16x16x32_bf16 v[48:51], v[228:231], v[156:159], v[48:51]
	s_and_b64 vcc, exec, s[18:19]
	s_nop 7
	s_branch .LBB0_769
.Lmyc_prelast_n:
	v_add_u32_e32 v12, s12, v206
	v_add_u32_e32 v13, s12, v10
	v_add_u32_e32 v14, s12, v208
	v_add_u32_e32 v15, s12, v11
	s_waitcnt vmcnt(6) lgkmcnt(0)
	s_barrier
	v_mfma_f32_16x16x32_bf16 v[108:111], v[160:163], v[144:147], v[108:111]
	ds_read_b128 v[112:115], v12
	v_mfma_f32_16x16x32_bf16 v[104:107], v[164:167], v[144:147], v[104:107]
	ds_read_b128 v[116:119], v12 offset:2048
	v_mfma_f32_16x16x32_bf16 v[100:103], v[216:219], v[144:147], v[100:103]
	ds_read_b128 v[120:123], v12 offset:4096
	v_mfma_f32_16x16x32_bf16 v[96:99], v[228:231], v[144:147], v[96:99]
	ds_read_b128 v[124:127], v12 offset:6144
	v_mfma_f32_16x16x32_bf16 v[92:95], v[160:163], v[148:151], v[92:95]
	ds_read_b128 v[128:131], v13
	v_mfma_f32_16x16x32_bf16 v[88:91], v[164:167], v[148:151], v[88:91]
	ds_read_b128 v[132:135], v13 offset:2048
	v_mfma_f32_16x16x32_bf16 v[84:87], v[216:219], v[148:151], v[84:87]
	ds_read_b128 v[136:139], v13 offset:4096
	v_mfma_f32_16x16x32_bf16 v[80:83], v[228:231], v[148:151], v[80:83]
	ds_read_b128 v[140:143], v13 offset:6144
	v_mfma_f32_16x16x32_bf16 v[76:79], v[160:163], v[152:155], v[76:79]
	v_mfma_f32_16x16x32_bf16 v[72:75], v[164:167], v[152:155], v[72:75]
	v_mfma_f32_16x16x32_bf16 v[68:71], v[216:219], v[152:155], v[68:71]
	v_mfma_f32_16x16x32_bf16 v[64:67], v[228:231], v[152:155], v[64:67]
	v_mfma_f32_16x16x32_bf16 v[60:63], v[160:163], v[156:159], v[60:63]
	v_mfma_f32_16x16x32_bf16 v[56:59], v[164:167], v[156:159], v[56:59]
	v_mfma_f32_16x16x32_bf16 v[52:55], v[216:219], v[156:159], v[52:55]
	v_mfma_f32_16x16x32_bf16 v[48:51], v[228:231], v[156:159], v[48:51]
	s_waitcnt lgkmcnt(0)
	v_mfma_f32_16x16x32_bf16 v[108:111], v[128:131], v[112:115], v[108:111]
	ds_read_b128 v[144:147], v14
	v_mfma_f32_16x16x32_bf16 v[104:107], v[132:135], v[112:115], v[104:107]
	ds_read_b128 v[148:151], v14 offset:2048
	v_mfma_f32_16x16x32_bf16 v[100:103], v[136:139], v[112:115], v[100:103]
	ds_read_b128 v[152:155], v14 offset:4096
	v_mfma_f32_16x16x32_bf16 v[96:99], v[140:143], v[112:115], v[96:99]
	ds_read_b128 v[156:159], v14 offset:6144
	v_mfma_f32_16x16x32_bf16 v[92:95], v[128:131], v[116:119], v[92:95]
	ds_read_b128 v[160:163], v15
	v_mfma_f32_16x16x32_bf16 v[88:91], v[132:135], v[116:119], v[88:91]
	ds_read_b128 v[164:167], v15 offset:2048
	v_mfma_f32_16x16x32_bf16 v[84:87], v[136:139], v[116:119], v[84:87]
	ds_read_b128 v[216:219], v15 offset:4096
	v_mfma_f32_16x16x32_bf16 v[80:83], v[140:143], v[116:119], v[80:83]
	ds_read_b128 v[228:231], v15 offset:6144
	v_mfma_f32_16x16x32_bf16 v[76:79], v[128:131], v[120:123], v[76:79]
	v_mfma_f32_16x16x32_bf16 v[72:75], v[132:135], v[120:123], v[72:75]
	v_mfma_f32_16x16x32_bf16 v[68:71], v[136:139], v[120:123], v[68:71]
	v_mfma_f32_16x16x32_bf16 v[64:67], v[140:143], v[120:123], v[64:67]
	v_mfma_f32_16x16x32_bf16 v[60:63], v[128:131], v[124:127], v[60:63]
	v_mfma_f32_16x16x32_bf16 v[56:59], v[132:135], v[124:127], v[56:59]
	v_mfma_f32_16x16x32_bf16 v[52:55], v[136:139], v[124:127], v[52:55]
	v_mfma_f32_16x16x32_bf16 v[48:51], v[140:143], v[124:127], v[48:51]
	s_mov_b32 s13, s12
	s_add_u32 s12, s12, 0xc000
	s_sub_u32 vcc_lo, s12, 0x24000
	s_cselect_b32 s12, s12, vcc_lo
	v_add_u32_e32 v12, s12, v206
	v_add_u32_e32 v13, s12, v10
	v_add_u32_e32 v14, s12, v208
	v_add_u32_e32 v15, s12, v11
	s_waitcnt vmcnt(0) lgkmcnt(0)
	s_barrier
	v_mfma_f32_16x16x32_bf16 v[108:111], v[160:163], v[144:147], v[108:111]
	ds_read_b128 v[112:115], v12
	v_mfma_f32_16x16x32_bf16 v[104:107], v[164:167], v[144:147], v[104:107]
	ds_read_b128 v[116:119], v12 offset:2048
	v_mfma_f32_16x16x32_bf16 v[100:103], v[216:219], v[144:147], v[100:103]
	ds_read_b128 v[120:123], v12 offset:4096
	v_mfma_f32_16x16x32_bf16 v[96:99], v[228:231], v[144:147], v[96:99]
	ds_read_b128 v[124:127], v12 offset:6144
	v_mfma_f32_16x16x32_bf16 v[92:95], v[160:163], v[148:151], v[92:95]
	ds_read_b128 v[128:131], v13
	v_mfma_f32_16x16x32_bf16 v[88:91], v[164:167], v[148:151], v[88:91]
	ds_read_b128 v[132:135], v13 offset:2048
	v_mfma_f32_16x16x32_bf16 v[84:87], v[216:219], v[148:151], v[84:87]
	ds_read_b128 v[136:139], v13 offset:4096
	v_mfma_f32_16x16x32_bf16 v[80:83], v[228:231], v[148:151], v[80:83]
	ds_read_b128 v[140:143], v13 offset:6144
	v_mfma_f32_16x16x32_bf16 v[76:79], v[160:163], v[152:155], v[76:79]
	v_mfma_f32_16x16x32_bf16 v[72:75], v[164:167], v[152:155], v[72:75]
	v_mfma_f32_16x16x32_bf16 v[68:71], v[216:219], v[152:155], v[68:71]
	v_mfma_f32_16x16x32_bf16 v[64:67], v[228:231], v[152:155], v[64:67]
	v_mfma_f32_16x16x32_bf16 v[60:63], v[160:163], v[156:159], v[60:63]
	v_mfma_f32_16x16x32_bf16 v[56:59], v[164:167], v[156:159], v[56:59]
	v_mfma_f32_16x16x32_bf16 v[52:55], v[216:219], v[156:159], v[52:55]
	v_mfma_f32_16x16x32_bf16 v[48:51], v[228:231], v[156:159], v[48:51]
	s_waitcnt lgkmcnt(0)
	v_mfma_f32_16x16x32_bf16 v[108:111], v[128:131], v[112:115], v[108:111]
	ds_read_b128 v[144:147], v14
	v_mfma_f32_16x16x32_bf16 v[104:107], v[132:135], v[112:115], v[104:107]
	ds_read_b128 v[148:151], v14 offset:2048
	v_mfma_f32_16x16x32_bf16 v[100:103], v[136:139], v[112:115], v[100:103]
	ds_read_b128 v[152:155], v14 offset:4096
	v_mfma_f32_16x16x32_bf16 v[96:99], v[140:143], v[112:115], v[96:99]
	ds_read_b128 v[156:159], v14 offset:6144
	v_mfma_f32_16x16x32_bf16 v[92:95], v[128:131], v[116:119], v[92:95]
	ds_read_b128 v[160:163], v15
	v_mfma_f32_16x16x32_bf16 v[88:91], v[132:135], v[116:119], v[88:91]
	ds_read_b128 v[164:167], v15 offset:2048
	v_mfma_f32_16x16x32_bf16 v[84:87], v[136:139], v[116:119], v[84:87]
	ds_read_b128 v[216:219], v15 offset:4096
	v_mfma_f32_16x16x32_bf16 v[80:83], v[140:143], v[116:119], v[80:83]
	ds_read_b128 v[228:231], v15 offset:6144
	v_mfma_f32_16x16x32_bf16 v[76:79], v[128:131], v[120:123], v[76:79]
	v_mfma_f32_16x16x32_bf16 v[72:75], v[132:135], v[120:123], v[72:75]
	v_mfma_f32_16x16x32_bf16 v[68:71], v[136:139], v[120:123], v[68:71]
	v_mfma_f32_16x16x32_bf16 v[64:67], v[140:143], v[120:123], v[64:67]
	v_mfma_f32_16x16x32_bf16 v[60:63], v[128:131], v[124:127], v[60:63]
	v_mfma_f32_16x16x32_bf16 v[56:59], v[132:135], v[124:127], v[56:59]
	v_mfma_f32_16x16x32_bf16 v[52:55], v[136:139], v[124:127], v[52:55]
	v_mfma_f32_16x16x32_bf16 v[48:51], v[140:143], v[124:127], v[48:51]
	s_mov_b32 s13, s12
	s_add_u32 s12, s12, 0xc000
	s_sub_u32 vcc_lo, s12, 0x24000
	s_cselect_b32 s12, s12, vcc_lo
	s_waitcnt lgkmcnt(0)
	v_mfma_f32_16x16x32_bf16 v[108:111], v[160:163], v[144:147], v[108:111]
	v_mfma_f32_16x16x32_bf16 v[104:107], v[164:167], v[144:147], v[104:107]
	v_mfma_f32_16x16x32_bf16 v[100:103], v[216:219], v[144:147], v[100:103]
	v_mfma_f32_16x16x32_bf16 v[96:99], v[228:231], v[144:147], v[96:99]
	v_mfma_f32_16x16x32_bf16 v[92:95], v[160:163], v[148:151], v[92:95]
	v_mfma_f32_16x16x32_bf16 v[88:91], v[164:167], v[148:151], v[88:91]
	v_mfma_f32_16x16x32_bf16 v[84:87], v[216:219], v[148:151], v[84:87]
	v_mfma_f32_16x16x32_bf16 v[80:83], v[228:231], v[148:151], v[80:83]
	v_mfma_f32_16x16x32_bf16 v[76:79], v[160:163], v[152:155], v[76:79]
	v_mfma_f32_16x16x32_bf16 v[72:75], v[164:167], v[152:155], v[72:75]
	v_mfma_f32_16x16x32_bf16 v[68:71], v[216:219], v[152:155], v[68:71]
	v_mfma_f32_16x16x32_bf16 v[64:67], v[228:231], v[152:155], v[64:67]
	v_mfma_f32_16x16x32_bf16 v[60:63], v[160:163], v[156:159], v[60:63]
	v_mfma_f32_16x16x32_bf16 v[56:59], v[164:167], v[156:159], v[56:59]
	v_mfma_f32_16x16x32_bf16 v[52:55], v[216:219], v[156:159], v[52:55]
	v_mfma_f32_16x16x32_bf16 v[48:51], v[228:231], v[156:159], v[48:51]
	s_and_b64 vcc, exec, s[18:19]
	s_nop 7
	s_branch .LBB0_769

.LBB0_1492:
	v_add_u32_e32 v12, s4, v215
	v_add_u32_e32 v13, s4, v10
	v_add_u32_e32 v14, s4, v217
	v_add_u32_e32 v15, s4, v11
	v_readfirstlane_b32 vcc_lo, v6
	s_nop 0
	s_add_u32 vcc_lo, vcc_lo, s5
	s_waitcnt vmcnt(6) lgkmcnt(0)
	s_barrier
	ds_read_b128 v[112:115], v12
	ds_read_b128 v[116:119], v12 offset:2048
	ds_read_b128 v[120:123], v12 offset:4096
	ds_read_b128 v[124:127], v12 offset:6144
	ds_read_b128 v[128:131], v13
	ds_read_b128 v[132:135], v13 offset:2048
	ds_read_b128 v[136:139], v13 offset:4096
	ds_read_b128 v[140:143], v13 offset:6144
	s_mov_b32 m0, vcc_lo
	s_nop 0
	global_load_lds_dwordx4 v0, s[98:99]
	s_add_u32 m0, m0, 0x2000
	s_nop 0
	global_load_lds_dwordx4 v1, s[98:99]
	s_add_u32 m0, m0, 0x2000
	s_nop 0
	global_load_lds_dwordx4 v2, s[98:99]
	s_add_u32 m0, m0, 0x2000
	s_nop 0
	global_load_lds_dwordx4 v3, s[98:99]
	s_add_u32 m0, vcc_lo, 0x8000
	s_nop 0
	global_load_lds_dwordx4 v4, s[100:101]
	s_add_u32 m0, m0, 0x2000
	s_nop 0
	global_load_lds_dwordx4 v5, s[100:101]
	s_add_u32 s98, s98, 0x80
	s_addc_u32 s99, s99, 0
	s_add_u32 s100, s100, 0x80
	s_addc_u32 s101, s101, 0
	s_waitcnt lgkmcnt(0)
	v_mfma_f32_16x16x32_bf16 v[108:111], v[128:131], v[112:115], v[108:111]
	ds_read_b128 v[144:147], v14
	v_mfma_f32_16x16x32_bf16 v[104:107], v[132:135], v[112:115], v[104:107]
	ds_read_b128 v[148:151], v14 offset:2048
	v_mfma_f32_16x16x32_bf16 v[100:103], v[136:139], v[112:115], v[100:103]
	ds_read_b128 v[152:155], v14 offset:4096
	v_mfma_f32_16x16x32_bf16 v[96:99], v[140:143], v[112:115], v[96:99]
	ds_read_b128 v[156:159], v14 offset:6144
	v_mfma_f32_16x16x32_bf16 v[92:95], v[128:131], v[116:119], v[92:95]
	ds_read_b128 v[160:163], v15
	v_mfma_f32_16x16x32_bf16 v[88:91], v[132:135], v[116:119], v[88:91]
	ds_read_b128 v[164:167], v15 offset:2048
	v_mfma_f32_16x16x32_bf16 v[84:87], v[136:139], v[116:119], v[84:87]
	ds_read_b128 v[224:227], v15 offset:4096
	v_mfma_f32_16x16x32_bf16 v[80:83], v[140:143], v[116:119], v[80:83]
	ds_read_b128 v[228:231], v15 offset:6144
	v_mfma_f32_16x16x32_bf16 v[76:79], v[128:131], v[120:123], v[76:79]
	v_mfma_f32_16x16x32_bf16 v[72:75], v[132:135], v[120:123], v[72:75]
	v_mfma_f32_16x16x32_bf16 v[68:71], v[136:139], v[120:123], v[68:71]
	v_mfma_f32_16x16x32_bf16 v[64:67], v[140:143], v[120:123], v[64:67]
	v_mfma_f32_16x16x32_bf16 v[60:63], v[128:131], v[124:127], v[60:63]
	v_mfma_f32_16x16x32_bf16 v[56:59], v[132:135], v[124:127], v[56:59]
	v_mfma_f32_16x16x32_bf16 v[52:55], v[136:139], v[124:127], v[52:55]
	v_mfma_f32_16x16x32_bf16 v[48:51], v[140:143], v[124:127], v[48:51]
	s_mov_b32 s5, s4
	s_add_u32 s4, s4, 0xc000
	s_sub_u32 vcc_lo, s4, 0x24000
	s_cselect_b32 s4, s4, vcc_lo
	s_mov_b32 s22, 1
.Lmyf_steady:
	v_add_u32_e32 v12, s4, v215
	v_add_u32_e32 v13, s4, v10
	v_add_u32_e32 v14, s4, v217
	v_add_u32_e32 v15, s4, v11
	v_readfirstlane_b32 vcc_lo, v6
	s_nop 0
	s_add_u32 vcc_lo, vcc_lo, s5
	s_waitcnt vmcnt(6) lgkmcnt(0)
	s_barrier
	v_mfma_f32_16x16x32_bf16 v[108:111], v[160:163], v[144:147], v[108:111]
	ds_read_b128 v[112:115], v12
	v_mfma_f32_16x16x32_bf16 v[104:107], v[164:167], v[144:147], v[104:107]
	ds_read_b128 v[116:119], v12 offset:2048
	v_mfma_f32_16x16x32_bf16 v[100:103], v[224:227], v[144:147], v[100:103]
	ds_read_b128 v[120:123], v12 offset:4096
	s_mov_b32 m0, vcc_lo
	v_mfma_f32_16x16x32_bf16 v[96:99], v[228:231], v[144:147], v[96:99]
	ds_read_b128 v[124:127], v12 offset:6144
	global_load_lds_dwordx4 v0, s[98:99]
	s_add_u32 m0, m0, 0x2000
	v_mfma_f32_16x16x32_bf16 v[92:95], v[160:163], v[148:151], v[92:95]
	ds_read_b128 v[128:131], v13
	global_load_lds_dwordx4 v1, s[98:99]
	s_add_u32 m0, m0, 0x2000
	v_mfma_f32_16x16x32_bf16 v[88:91], v[164:167], v[148:151], v[88:91]
	ds_read_b128 v[132:135], v13 offset:2048
	global_load_lds_dwordx4 v2, s[98:99]
	s_add_u32 m0, m0, 0x2000
	v_mfma_f32_16x16x32_bf16 v[84:87], v[224:227], v[148:151], v[84:87]
	ds_read_b128 v[136:139], v13 offset:4096
	global_load_lds_dwordx4 v3, s[98:99]
	s_add_u32 m0, vcc_lo, 0x8000
	v_mfma_f32_16x16x32_bf16 v[80:83], v[228:231], v[148:151], v[80:83]
	ds_read_b128 v[140:143], v13 offset:6144
	global_load_lds_dwordx4 v4, s[100:101]
	s_add_u32 m0, m0, 0x2000
	v_mfma_f32_16x16x32_bf16 v[76:79], v[160:163], v[152:155], v[76:79]
	global_load_lds_dwordx4 v5, s[100:101]
	v_mfma_f32_16x16x32_bf16 v[72:75], v[164:167], v[152:155], v[72:75]
	s_add_u32 s98, s98, 0x80
	s_addc_u32 s99, s99, 0
	s_add_u32 s100, s100, 0x80
	s_addc_u32 s101, s101, 0
	v_mfma_f32_16x16x32_bf16 v[68:71], v[224:227], v[152:155], v[68:71]
	v_mfma_f32_16x16x32_bf16 v[64:67], v[228:231], v[152:155], v[64:67]
	v_mfma_f32_16x16x32_bf16 v[60:63], v[160:163], v[156:159], v[60:63]
	v_mfma_f32_16x16x32_bf16 v[56:59], v[164:167], v[156:159], v[56:59]
	v_mfma_f32_16x16x32_bf16 v[52:55], v[224:227], v[156:159], v[52:55]
	v_mfma_f32_16x16x32_bf16 v[48:51], v[228:231], v[156:159], v[48:51]
	s_waitcnt lgkmcnt(0)
	v_mfma_f32_16x16x32_bf16 v[108:111], v[128:131], v[112:115], v[108:111]
	ds_read_b128 v[144:147], v14
	v_mfma_f32_16x16x32_bf16 v[104:107], v[132:135], v[112:115], v[104:107]
	ds_read_b128 v[148:151], v14 offset:2048
	v_mfma_f32_16x16x32_bf16 v[100:103], v[136:139], v[112:115], v[100:103]
	ds_read_b128 v[152:155], v14 offset:4096
	v_mfma_f32_16x16x32_bf16 v[96:99], v[140:143], v[112:115], v[96:99]
	ds_read_b128 v[156:159], v14 offset:6144
	v_mfma_f32_16x16x32_bf16 v[92:95], v[128:131], v[116:119], v[92:95]
	ds_read_b128 v[160:163], v15
	v_mfma_f32_16x16x32_bf16 v[88:91], v[132:135], v[116:119], v[88:91]
	ds_read_b128 v[164:167], v15 offset:2048
	v_mfma_f32_16x16x32_bf16 v[84:87], v[136:139], v[116:119], v[84:87]
	ds_read_b128 v[224:227], v15 offset:4096
	v_mfma_f32_16x16x32_bf16 v[80:83], v[140:143], v[116:119], v[80:83]
	ds_read_b128 v[228:231], v15 offset:6144
	v_mfma_f32_16x16x32_bf16 v[76:79], v[128:131], v[120:123], v[76:79]
	v_mfma_f32_16x16x32_bf16 v[72:75], v[132:135], v[120:123], v[72:75]
	v_mfma_f32_16x16x32_bf16 v[68:71], v[136:139], v[120:123], v[68:71]
	v_mfma_f32_16x16x32_bf16 v[64:67], v[140:143], v[120:123], v[64:67]
	v_mfma_f32_16x16x32_bf16 v[60:63], v[128:131], v[124:127], v[60:63]
	v_mfma_f32_16x16x32_bf16 v[56:59], v[132:135], v[124:127], v[56:59]
	v_mfma_f32_16x16x32_bf16 v[52:55], v[136:139], v[124:127], v[52:55]
	v_mfma_f32_16x16x32_bf16 v[48:51], v[140:143], v[124:127], v[48:51]
	s_mov_b32 s5, s4
	s_add_u32 s4, s4, 0xc000
	s_sub_u32 vcc_lo, s4, 0x24000
	s_cselect_b32 s4, s4, vcc_lo
	s_add_i32 s22, s22, 1
	s_cmp_lt_u32 s22, 14
	s_cbranch_scc1 .Lmyf_steady
	s_andn2_b64 vcc, exec, s[8:9]
	s_cbranch_vccnz .Lmyf_prelast_n
	v_readlane_b32 s98, v250, 0
	v_readlane_b32 s99, v250, 1
	v_readlane_b32 s100, v250, 2
	v_readlane_b32 s101, v250, 3
	v_add_u32_e32 v12, s4, v215
	v_add_u32_e32 v13, s4, v10
	v_add_u32_e32 v14, s4, v217
	v_add_u32_e32 v15, s4, v11
	v_readfirstlane_b32 vcc_lo, v6
	s_nop 0
	s_add_u32 vcc_lo, vcc_lo, s5
	s_waitcnt vmcnt(6) lgkmcnt(0)
	s_barrier
	v_mfma_f32_16x16x32_bf16 v[108:111], v[160:163], v[144:147], v[108:111]
	ds_read_b128 v[112:115], v12
	v_mfma_f32_16x16x32_bf16 v[104:107], v[164:167], v[144:147], v[104:107]
	ds_read_b128 v[116:119], v12 offset:2048
	v_mfma_f32_16x16x32_bf16 v[100:103], v[224:227], v[144:147], v[100:103]
	ds_read_b128 v[120:123], v12 offset:4096
	s_mov_b32 m0, vcc_lo
	v_mfma_f32_16x16x32_bf16 v[96:99], v[228:231], v[144:147], v[96:99]
	ds_read_b128 v[124:127], v12 offset:6144
	global_load_lds_dwordx4 v0, s[98:99]
	s_add_u32 m0, m0, 0x2000
	v_mfma_f32_16x16x32_bf16 v[92:95], v[160:163], v[148:151], v[92:95]
	ds_read_b128 v[128:131], v13
	global_load_lds_dwordx4 v1, s[98:99]
	s_add_u32 m0, m0, 0x2000
	v_mfma_f32_16x16x32_bf16 v[88:91], v[164:167], v[148:151], v[88:91]
	ds_read_b128 v[132:135], v13 offset:2048
	global_load_lds_dwordx4 v2, s[98:99]
	s_add_u32 m0, m0, 0x2000
	v_mfma_f32_16x16x32_bf16 v[84:87], v[224:227], v[148:151], v[84:87]
	ds_read_b128 v[136:139], v13 offset:4096
	global_load_lds_dwordx4 v3, s[98:99]
	s_add_u32 m0, vcc_lo, 0x8000
	v_mfma_f32_16x16x32_bf16 v[80:83], v[228:231], v[148:151], v[80:83]
	ds_read_b128 v[140:143], v13 offset:6144
	global_load_lds_dwordx4 v4, s[100:101]
	s_add_u32 m0, m0, 0x2000
	v_mfma_f32_16x16x32_bf16 v[76:79], v[160:163], v[152:155], v[76:79]
	global_load_lds_dwordx4 v5, s[100:101]
	v_mfma_f32_16x16x32_bf16 v[72:75], v[164:167], v[152:155], v[72:75]
	s_add_u32 s98, s98, 0x80
	s_addc_u32 s99, s99, 0
	s_add_u32 s100, s100, 0x80
	s_addc_u32 s101, s101, 0
	v_mfma_f32_16x16x32_bf16 v[68:71], v[224:227], v[152:155], v[68:71]
	v_mfma_f32_16x16x32_bf16 v[64:67], v[228:231], v[152:155], v[64:67]
	v_mfma_f32_16x16x32_bf16 v[60:63], v[160:163], v[156:159], v[60:63]
	v_mfma_f32_16x16x32_bf16 v[56:59], v[164:167], v[156:159], v[56:59]
	v_mfma_f32_16x16x32_bf16 v[52:55], v[224:227], v[156:159], v[52:55]
	v_mfma_f32_16x16x32_bf16 v[48:51], v[228:231], v[156:159], v[48:51]
	s_waitcnt lgkmcnt(0)
	v_mfma_f32_16x16x32_bf16 v[108:111], v[128:131], v[112:115], v[108:111]
	ds_read_b128 v[144:147], v14
	v_mfma_f32_16x16x32_bf16 v[104:107], v[132:135], v[112:115], v[104:107]
	ds_read_b128 v[148:151], v14 offset:2048
	v_mfma_f32_16x16x32_bf16 v[100:103], v[136:139], v[112:115], v[100:103]
	ds_read_b128 v[152:155], v14 offset:4096
	v_mfma_f32_16x16x32_bf16 v[96:99], v[140:143], v[112:115], v[96:99]
	ds_read_b128 v[156:159], v14 offset:6144
	v_mfma_f32_16x16x32_bf16 v[92:95], v[128:131], v[116:119], v[92:95]
	ds_read_b128 v[160:163], v15
	v_mfma_f32_16x16x32_bf16 v[88:91], v[132:135], v[116:119], v[88:91]
	ds_read_b128 v[164:167], v15 offset:2048
	v_mfma_f32_16x16x32_bf16 v[84:87], v[136:139], v[116:119], v[84:87]
	ds_read_b128 v[224:227], v15 offset:4096
	v_mfma_f32_16x16x32_bf16 v[80:83], v[140:143], v[116:119], v[80:83]
	ds_read_b128 v[228:231], v15 offset:6144
	v_mfma_f32_16x16x32_bf16 v[76:79], v[128:131], v[120:123], v[76:79]
	v_mfma_f32_16x16x32_bf16 v[72:75], v[132:135], v[120:123], v[72:75]
	v_mfma_f32_16x16x32_bf16 v[68:71], v[136:139], v[120:123], v[68:71]
	v_mfma_f32_16x16x32_bf16 v[64:67], v[140:143], v[120:123], v[64:67]
	v_mfma_f32_16x16x32_bf16 v[60:63], v[128:131], v[124:127], v[60:63]
	v_mfma_f32_16x16x32_bf16 v[56:59], v[132:135], v[124:127], v[56:59]
	v_mfma_f32_16x16x32_bf16 v[52:55], v[136:139], v[124:127], v[52:55]
	v_mfma_f32_16x16x32_bf16 v[48:51], v[140:143], v[124:127], v[48:51]
	s_mov_b32 s5, s4
	s_add_u32 s4, s4, 0xc000
	s_sub_u32 vcc_lo, s4, 0x24000
	s_cselect_b32 s4, s4, vcc_lo
	v_add_u32_e32 v12, s4, v215
	v_add_u32_e32 v13, s4, v10
	v_add_u32_e32 v14, s4, v217
	v_add_u32_e32 v15, s4, v11
	v_readfirstlane_b32 vcc_lo, v6
	s_nop 0
	s_add_u32 vcc_lo, vcc_lo, s5
	s_waitcnt vmcnt(6) lgkmcnt(0)
	s_barrier
	v_mfma_f32_16x16x32_bf16 v[108:111], v[160:163], v[144:147], v[108:111]
	ds_read_b128 v[112:115], v12
	v_mfma_f32_16x16x32_bf16 v[104:107], v[164:167], v[144:147], v[104:107]
	ds_read_b128 v[116:119], v12 offset:2048
	v_mfma_f32_16x16x32_bf16 v[100:103], v[224:227], v[144:147], v[100:103]
	ds_read_b128 v[120:123], v12 offset:4096
	s_mov_b32 m0, vcc_lo
	v_mfma_f32_16x16x32_bf16 v[96:99], v[228:231], v[144:147], v[96:99]
	ds_read_b128 v[124:127], v12 offset:6144
	global_load_lds_dwordx4 v0, s[98:99]
	s_add_u32 m0, m0, 0x2000
	v_mfma_f32_16x16x32_bf16 v[92:95], v[160:163], v[148:151], v[92:95]
	ds_read_b128 v[128:131], v13
	global_load_lds_dwordx4 v1, s[98:99]
	s_add_u32 m0, m0, 0x2000
	v_mfma_f32_16x16x32_bf16 v[88:91], v[164:167], v[148:151], v[88:91]
	ds_read_b128 v[132:135], v13 offset:2048
	global_load_lds_dwordx4 v2, s[98:99]
	s_add_u32 m0, m0, 0x2000
	v_mfma_f32_16x16x32_bf16 v[84:87], v[224:227], v[148:151], v[84:87]
	ds_read_b128 v[136:139], v13 offset:4096
	global_load_lds_dwordx4 v3, s[98:99]
	s_add_u32 m0, vcc_lo, 0x8000
	v_mfma_f32_16x16x32_bf16 v[80:83], v[228:231], v[148:151], v[80:83]
	ds_read_b128 v[140:143], v13 offset:6144
	global_load_lds_dwordx4 v4, s[100:101]
	s_add_u32 m0, m0, 0x2000
	v_mfma_f32_16x16x32_bf16 v[76:79], v[160:163], v[152:155], v[76:79]
	global_load_lds_dwordx4 v5, s[100:101]
	v_mfma_f32_16x16x32_bf16 v[72:75], v[164:167], v[152:155], v[72:75]
	s_add_u32 s98, s98, 0x80
	s_addc_u32 s99, s99, 0
	s_add_u32 s100, s100, 0x80
	s_addc_u32 s101, s101, 0
	v_mfma_f32_16x16x32_bf16 v[68:71], v[224:227], v[152:155], v[68:71]
	v_mfma_f32_16x16x32_bf16 v[64:67], v[228:231], v[152:155], v[64:67]
	v_mfma_f32_16x16x32_bf16 v[60:63], v[160:163], v[156:159], v[60:63]
	v_mfma_f32_16x16x32_bf16 v[56:59], v[164:167], v[156:159], v[56:59]
	v_mfma_f32_16x16x32_bf16 v[52:55], v[224:227], v[156:159], v[52:55]
	v_mfma_f32_16x16x32_bf16 v[48:51], v[228:231], v[156:159], v[48:51]
	s_waitcnt lgkmcnt(0)
	v_mfma_f32_16x16x32_bf16 v[108:111], v[128:131], v[112:115], v[108:111]
	ds_read_b128 v[144:147], v14
	v_mfma_f32_16x16x32_bf16 v[104:107], v[132:135], v[112:115], v[104:107]
	ds_read_b128 v[148:151], v14 offset:2048
	v_mfma_f32_16x16x32_bf16 v[100:103], v[136:139], v[112:115], v[100:103]
	ds_read_b128 v[152:155], v14 offset:4096
	v_mfma_f32_16x16x32_bf16 v[96:99], v[140:143], v[112:115], v[96:99]
	ds_read_b128 v[156:159], v14 offset:6144
	v_mfma_f32_16x16x32_bf16 v[92:95], v[128:131], v[116:119], v[92:95]
	ds_read_b128 v[160:163], v15
	v_mfma_f32_16x16x32_bf16 v[88:91], v[132:135], v[116:119], v[88:91]
	ds_read_b128 v[164:167], v15 offset:2048
	v_mfma_f32_16x16x32_bf16 v[84:87], v[136:139], v[116:119], v[84:87]
	ds_read_b128 v[224:227], v15 offset:4096
	v_mfma_f32_16x16x32_bf16 v[80:83], v[140:143], v[116:119], v[80:83]
	ds_read_b128 v[228:231], v15 offset:6144
	v_mfma_f32_16x16x32_bf16 v[76:79], v[128:131], v[120:123], v[76:79]
	v_mfma_f32_16x16x32_bf16 v[72:75], v[132:135], v[120:123], v[72:75]
	v_mfma_f32_16x16x32_bf16 v[68:71], v[136:139], v[120:123], v[68:71]
	v_mfma_f32_16x16x32_bf16 v[64:67], v[140:143], v[120:123], v[64:67]
	v_mfma_f32_16x16x32_bf16 v[60:63], v[128:131], v[124:127], v[60:63]
	v_mfma_f32_16x16x32_bf16 v[56:59], v[132:135], v[124:127], v[56:59]
	v_mfma_f32_16x16x32_bf16 v[52:55], v[136:139], v[124:127], v[52:55]
	v_mfma_f32_16x16x32_bf16 v[48:51], v[140:143], v[124:127], v[48:51]
	s_mov_b32 s5, s4
	s_add_u32 s4, s4, 0xc000
	s_sub_u32 vcc_lo, s4, 0x24000
	s_cselect_b32 s4, s4, vcc_lo
	s_waitcnt lgkmcnt(0)
	v_mfma_f32_16x16x32_bf16 v[108:111], v[160:163], v[144:147], v[108:111]
	v_mfma_f32_16x16x32_bf16 v[104:107], v[164:167], v[144:147], v[104:107]
	v_mfma_f32_16x16x32_bf16 v[100:103], v[224:227], v[144:147], v[100:103]
	v_mfma_f32_16x16x32_bf16 v[96:99], v[228:231], v[144:147], v[96:99]
	v_mfma_f32_16x16x32_bf16 v[92:95], v[160:163], v[148:151], v[92:95]
	v_mfma_f32_16x16x32_bf16 v[88:91], v[164:167], v[148:151], v[88:91]
	v_mfma_f32_16x16x32_bf16 v[84:87], v[224:227], v[148:151], v[84:87]
	v_mfma_f32_16x16x32_bf16 v[80:83], v[228:231], v[148:151], v[80:83]
	v_mfma_f32_16x16x32_bf16 v[76:79], v[160:163], v[152:155], v[76:79]
	v_mfma_f32_16x16x32_bf16 v[72:75], v[164:167], v[152:155], v[72:75]
	v_mfma_f32_16x16x32_bf16 v[68:71], v[224:227], v[152:155], v[68:71]
	v_mfma_f32_16x16x32_bf16 v[64:67], v[228:231], v[152:155], v[64:67]
	v_mfma_f32_16x16x32_bf16 v[60:63], v[160:163], v[156:159], v[60:63]
	v_mfma_f32_16x16x32_bf16 v[56:59], v[164:167], v[156:159], v[56:59]
	v_mfma_f32_16x16x32_bf16 v[52:55], v[224:227], v[156:159], v[52:55]
	v_mfma_f32_16x16x32_bf16 v[48:51], v[228:231], v[156:159], v[48:51]
	s_and_b64 vcc, exec, s[10:11]
	s_nop 7
	s_branch .LBB0_1487
.Lmyf_prelast_n:
	v_add_u32_e32 v12, s4, v215
	v_add_u32_e32 v13, s4, v10
	v_add_u32_e32 v14, s4, v217
	v_add_u32_e32 v15, s4, v11
	s_waitcnt vmcnt(6) lgkmcnt(0)
	s_barrier
	v_mfma_f32_16x16x32_bf16 v[108:111], v[160:163], v[144:147], v[108:111]
	ds_read_b128 v[112:115], v12
	v_mfma_f32_16x16x32_bf16 v[104:107], v[164:167], v[144:147], v[104:107]
	ds_read_b128 v[116:119], v12 offset:2048
	v_mfma_f32_16x16x32_bf16 v[100:103], v[224:227], v[144:147], v[100:103]
	ds_read_b128 v[120:123], v12 offset:4096
	v_mfma_f32_16x16x32_bf16 v[96:99], v[228:231], v[144:147], v[96:99]
	ds_read_b128 v[124:127], v12 offset:6144
	v_mfma_f32_16x16x32_bf16 v[92:95], v[160:163], v[148:151], v[92:95]
	ds_read_b128 v[128:131], v13
	v_mfma_f32_16x16x32_bf16 v[88:91], v[164:167], v[148:151], v[88:91]
	ds_read_b128 v[132:135], v13 offset:2048
	v_mfma_f32_16x16x32_bf16 v[84:87], v[224:227], v[148:151], v[84:87]
	ds_read_b128 v[136:139], v13 offset:4096
	v_mfma_f32_16x16x32_bf16 v[80:83], v[228:231], v[148:151], v[80:83]
	ds_read_b128 v[140:143], v13 offset:6144
	v_mfma_f32_16x16x32_bf16 v[76:79], v[160:163], v[152:155], v[76:79]
	v_mfma_f32_16x16x32_bf16 v[72:75], v[164:167], v[152:155], v[72:75]
	v_mfma_f32_16x16x32_bf16 v[68:71], v[224:227], v[152:155], v[68:71]
	v_mfma_f32_16x16x32_bf16 v[64:67], v[228:231], v[152:155], v[64:67]
	v_mfma_f32_16x16x32_bf16 v[60:63], v[160:163], v[156:159], v[60:63]
	v_mfma_f32_16x16x32_bf16 v[56:59], v[164:167], v[156:159], v[56:59]
	v_mfma_f32_16x16x32_bf16 v[52:55], v[224:227], v[156:159], v[52:55]
	v_mfma_f32_16x16x32_bf16 v[48:51], v[228:231], v[156:159], v[48:51]
	s_waitcnt lgkmcnt(0)
	v_mfma_f32_16x16x32_bf16 v[108:111], v[128:131], v[112:115], v[108:111]
	ds_read_b128 v[144:147], v14
	v_mfma_f32_16x16x32_bf16 v[104:107], v[132:135], v[112:115], v[104:107]
	ds_read_b128 v[148:151], v14 offset:2048
	v_mfma_f32_16x16x32_bf16 v[100:103], v[136:139], v[112:115], v[100:103]
	ds_read_b128 v[152:155], v14 offset:4096
	v_mfma_f32_16x16x32_bf16 v[96:99], v[140:143], v[112:115], v[96:99]
	ds_read_b128 v[156:159], v14 offset:6144
	v_mfma_f32_16x16x32_bf16 v[92:95], v[128:131], v[116:119], v[92:95]
	ds_read_b128 v[160:163], v15
	v_mfma_f32_16x16x32_bf16 v[88:91], v[132:135], v[116:119], v[88:91]
	ds_read_b128 v[164:167], v15 offset:2048
	v_mfma_f32_16x16x32_bf16 v[84:87], v[136:139], v[116:119], v[84:87]
	ds_read_b128 v[224:227], v15 offset:4096
	v_mfma_f32_16x16x32_bf16 v[80:83], v[140:143], v[116:119], v[80:83]
	ds_read_b128 v[228:231], v15 offset:6144
	v_mfma_f32_16x16x32_bf16 v[76:79], v[128:131], v[120:123], v[76:79]
	v_mfma_f32_16x16x32_bf16 v[72:75], v[132:135], v[120:123], v[72:75]
	v_mfma_f32_16x16x32_bf16 v[68:71], v[136:139], v[120:123], v[68:71]
	v_mfma_f32_16x16x32_bf16 v[64:67], v[140:143], v[120:123], v[64:67]
	v_mfma_f32_16x16x32_bf16 v[60:63], v[128:131], v[124:127], v[60:63]
	v_mfma_f32_16x16x32_bf16 v[56:59], v[132:135], v[124:127], v[56:59]
	v_mfma_f32_16x16x32_bf16 v[52:55], v[136:139], v[124:127], v[52:55]
	v_mfma_f32_16x16x32_bf16 v[48:51], v[140:143], v[124:127], v[48:51]
	s_mov_b32 s5, s4
	s_add_u32 s4, s4, 0xc000
	s_sub_u32 vcc_lo, s4, 0x24000
	s_cselect_b32 s4, s4, vcc_lo
	v_add_u32_e32 v12, s4, v215
	v_add_u32_e32 v13, s4, v10
	v_add_u32_e32 v14, s4, v217
	v_add_u32_e32 v15, s4, v11
	s_waitcnt vmcnt(0) lgkmcnt(0)
	s_barrier
	v_mfma_f32_16x16x32_bf16 v[108:111], v[160:163], v[144:147], v[108:111]
	ds_read_b128 v[112:115], v12
	v_mfma_f32_16x16x32_bf16 v[104:107], v[164:167], v[144:147], v[104:107]
	ds_read_b128 v[116:119], v12 offset:2048
	v_mfma_f32_16x16x32_bf16 v[100:103], v[224:227], v[144:147], v[100:103]
	ds_read_b128 v[120:123], v12 offset:4096
	v_mfma_f32_16x16x32_bf16 v[96:99], v[228:231], v[144:147], v[96:99]
	ds_read_b128 v[124:127], v12 offset:6144
	v_mfma_f32_16x16x32_bf16 v[92:95], v[160:163], v[148:151], v[92:95]
	ds_read_b128 v[128:131], v13
	v_mfma_f32_16x16x32_bf16 v[88:91], v[164:167], v[148:151], v[88:91]
	ds_read_b128 v[132:135], v13 offset:2048
	v_mfma_f32_16x16x32_bf16 v[84:87], v[224:227], v[148:151], v[84:87]
	ds_read_b128 v[136:139], v13 offset:4096
	v_mfma_f32_16x16x32_bf16 v[80:83], v[228:231], v[148:151], v[80:83]
	ds_read_b128 v[140:143], v13 offset:6144
	v_mfma_f32_16x16x32_bf16 v[76:79], v[160:163], v[152:155], v[76:79]
	v_mfma_f32_16x16x32_bf16 v[72:75], v[164:167], v[152:155], v[72:75]
	v_mfma_f32_16x16x32_bf16 v[68:71], v[224:227], v[152:155], v[68:71]
	v_mfma_f32_16x16x32_bf16 v[64:67], v[228:231], v[152:155], v[64:67]
	v_mfma_f32_16x16x32_bf16 v[60:63], v[160:163], v[156:159], v[60:63]
	v_mfma_f32_16x16x32_bf16 v[56:59], v[164:167], v[156:159], v[56:59]
	v_mfma_f32_16x16x32_bf16 v[52:55], v[224:227], v[156:159], v[52:55]
	v_mfma_f32_16x16x32_bf16 v[48:51], v[228:231], v[156:159], v[48:51]
	s_waitcnt lgkmcnt(0)
	v_mfma_f32_16x16x32_bf16 v[108:111], v[128:131], v[112:115], v[108:111]
	ds_read_b128 v[144:147], v14
	v_mfma_f32_16x16x32_bf16 v[104:107], v[132:135], v[112:115], v[104:107]
	ds_read_b128 v[148:151], v14 offset:2048
	v_mfma_f32_16x16x32_bf16 v[100:103], v[136:139], v[112:115], v[100:103]
	ds_read_b128 v[152:155], v14 offset:4096
	v_mfma_f32_16x16x32_bf16 v[96:99], v[140:143], v[112:115], v[96:99]
	ds_read_b128 v[156:159], v14 offset:6144
	v_mfma_f32_16x16x32_bf16 v[92:95], v[128:131], v[116:119], v[92:95]
	ds_read_b128 v[160:163], v15
	v_mfma_f32_16x16x32_bf16 v[88:91], v[132:135], v[116:119], v[88:91]
	ds_read_b128 v[164:167], v15 offset:2048
	v_mfma_f32_16x16x32_bf16 v[84:87], v[136:139], v[116:119], v[84:87]
	ds_read_b128 v[224:227], v15 offset:4096
	v_mfma_f32_16x16x32_bf16 v[80:83], v[140:143], v[116:119], v[80:83]
	ds_read_b128 v[228:231], v15 offset:6144
	v_mfma_f32_16x16x32_bf16 v[76:79], v[128:131], v[120:123], v[76:79]
	v_mfma_f32_16x16x32_bf16 v[72:75], v[132:135], v[120:123], v[72:75]
	v_mfma_f32_16x16x32_bf16 v[68:71], v[136:139], v[120:123], v[68:71]
	v_mfma_f32_16x16x32_bf16 v[64:67], v[140:143], v[120:123], v[64:67]
	v_mfma_f32_16x16x32_bf16 v[60:63], v[128:131], v[124:127], v[60:63]
	v_mfma_f32_16x16x32_bf16 v[56:59], v[132:135], v[124:127], v[56:59]
	v_mfma_f32_16x16x32_bf16 v[52:55], v[136:139], v[124:127], v[52:55]
	v_mfma_f32_16x16x32_bf16 v[48:51], v[140:143], v[124:127], v[48:51]
	s_mov_b32 s5, s4
	s_add_u32 s4, s4, 0xc000
	s_sub_u32 vcc_lo, s4, 0x24000
	s_cselect_b32 s4, s4, vcc_lo
	s_waitcnt lgkmcnt(0)
	v_mfma_f32_16x16x32_bf16 v[108:111], v[160:163], v[144:147], v[108:111]
	v_mfma_f32_16x16x32_bf16 v[104:107], v[164:167], v[144:147], v[104:107]
	v_mfma_f32_16x16x32_bf16 v[100:103], v[224:227], v[144:147], v[100:103]
	v_mfma_f32_16x16x32_bf16 v[96:99], v[228:231], v[144:147], v[96:99]
	v_mfma_f32_16x16x32_bf16 v[92:95], v[160:163], v[148:151], v[92:95]
	v_mfma_f32_16x16x32_bf16 v[88:91], v[164:167], v[148:151], v[88:91]
	v_mfma_f32_16x16x32_bf16 v[84:87], v[224:227], v[148:151], v[84:87]
	v_mfma_f32_16x16x32_bf16 v[80:83], v[228:231], v[148:151], v[80:83]
	v_mfma_f32_16x16x32_bf16 v[76:79], v[160:163], v[152:155], v[76:79]
	v_mfma_f32_16x16x32_bf16 v[72:75], v[164:167], v[152:155], v[72:75]
	v_mfma_f32_16x16x32_bf16 v[68:71], v[224:227], v[152:155], v[68:71]
	v_mfma_f32_16x16x32_bf16 v[64:67], v[228:231], v[152:155], v[64:67]
	v_mfma_f32_16x16x32_bf16 v[60:63], v[160:163], v[156:159], v[60:63]
	v_mfma_f32_16x16x32_bf16 v[56:59], v[164:167], v[156:159], v[56:59]
	v_mfma_f32_16x16x32_bf16 v[52:55], v[224:227], v[156:159], v[52:55]
	v_mfma_f32_16x16x32_bf16 v[48:51], v[228:231], v[156:159], v[48:51]
	s_and_b64 vcc, exec, s[10:11]
	s_nop 7
	s_branch .LBB0_1487

.LBB0_1564:
	v_add_u32_e32 v12, s4, v214
	v_add_u32_e32 v13, s4, v10
	v_add_u32_e32 v14, s4, v216
	v_add_u32_e32 v15, s4, v11
	v_readfirstlane_b32 vcc_lo, v6
	s_nop 0
	s_add_u32 vcc_lo, vcc_lo, s5
	s_waitcnt vmcnt(6) lgkmcnt(0)
	s_barrier
	ds_read_b128 v[112:115], v12
	ds_read_b128 v[116:119], v12 offset:2048
	ds_read_b128 v[120:123], v12 offset:4096
	ds_read_b128 v[124:127], v12 offset:6144
	ds_read_b128 v[128:131], v13
	ds_read_b128 v[132:135], v13 offset:2048
	ds_read_b128 v[136:139], v13 offset:4096
	ds_read_b128 v[140:143], v13 offset:6144
	s_mov_b32 m0, vcc_lo
	s_nop 0
	global_load_lds_dwordx4 v0, s[98:99]
	s_add_u32 m0, m0, 0x2000
	s_nop 0
	global_load_lds_dwordx4 v1, s[98:99]
	s_add_u32 m0, m0, 0x2000
	s_nop 0
	global_load_lds_dwordx4 v2, s[98:99]
	s_add_u32 m0, m0, 0x2000
	s_nop 0
	global_load_lds_dwordx4 v3, s[98:99]
	s_add_u32 m0, vcc_lo, 0x8000
	s_nop 0
	global_load_lds_dwordx4 v4, s[100:101]
	s_add_u32 m0, m0, 0x2000
	s_nop 0
	global_load_lds_dwordx4 v5, s[100:101]
	s_add_u32 s98, s98, 0x80
	s_addc_u32 s99, s99, 0
	s_add_u32 s100, s100, 0x80
	s_addc_u32 s101, s101, 0
	s_waitcnt lgkmcnt(0)
	v_mfma_f32_16x16x32_bf16 v[108:111], v[112:115], v[128:131], v[108:111]
	ds_read_b128 v[144:147], v14
	v_mfma_f32_16x16x32_bf16 v[104:107], v[112:115], v[132:135], v[104:107]
	ds_read_b128 v[148:151], v14 offset:2048
	v_mfma_f32_16x16x32_bf16 v[100:103], v[112:115], v[136:139], v[100:103]
	ds_read_b128 v[152:155], v14 offset:4096
	v_mfma_f32_16x16x32_bf16 v[96:99], v[112:115], v[140:143], v[96:99]
	ds_read_b128 v[156:159], v14 offset:6144
	v_mfma_f32_16x16x32_bf16 v[92:95], v[116:119], v[128:131], v[92:95]
	ds_read_b128 v[160:163], v15
	v_mfma_f32_16x16x32_bf16 v[88:91], v[116:119], v[132:135], v[88:91]
	ds_read_b128 v[164:167], v15 offset:2048
	v_mfma_f32_16x16x32_bf16 v[84:87], v[116:119], v[136:139], v[84:87]
	ds_read_b128 v[224:227], v15 offset:4096
	v_mfma_f32_16x16x32_bf16 v[80:83], v[116:119], v[140:143], v[80:83]
	ds_read_b128 v[228:231], v15 offset:6144
	v_mfma_f32_16x16x32_bf16 v[76:79], v[120:123], v[128:131], v[76:79]
	v_mfma_f32_16x16x32_bf16 v[72:75], v[120:123], v[132:135], v[72:75]
	v_mfma_f32_16x16x32_bf16 v[68:71], v[120:123], v[136:139], v[68:71]
	v_mfma_f32_16x16x32_bf16 v[64:67], v[120:123], v[140:143], v[64:67]
	v_mfma_f32_16x16x32_bf16 v[60:63], v[124:127], v[128:131], v[60:63]
	v_mfma_f32_16x16x32_bf16 v[56:59], v[124:127], v[132:135], v[56:59]
	v_mfma_f32_16x16x32_bf16 v[52:55], v[124:127], v[136:139], v[52:55]
	v_mfma_f32_16x16x32_bf16 v[48:51], v[124:127], v[140:143], v[48:51]
	s_mov_b32 s5, s4
	s_add_u32 s4, s4, 0xc000
	s_sub_u32 vcc_lo, s4, 0x24000
	s_cselect_b32 s4, s4, vcc_lo
	s_mov_b32 s19, 1
.Lmyg_steady:
	v_add_u32_e32 v12, s4, v214
	v_add_u32_e32 v13, s4, v10
	v_add_u32_e32 v14, s4, v216
	v_add_u32_e32 v15, s4, v11
	v_readfirstlane_b32 vcc_lo, v6
	s_nop 0
	s_add_u32 vcc_lo, vcc_lo, s5
	s_waitcnt vmcnt(6) lgkmcnt(0)
	s_barrier
	v_mfma_f32_16x16x32_bf16 v[108:111], v[144:147], v[160:163], v[108:111]
	ds_read_b128 v[112:115], v12
	v_mfma_f32_16x16x32_bf16 v[104:107], v[144:147], v[164:167], v[104:107]
	ds_read_b128 v[116:119], v12 offset:2048
	v_mfma_f32_16x16x32_bf16 v[100:103], v[144:147], v[224:227], v[100:103]
	ds_read_b128 v[120:123], v12 offset:4096
	s_mov_b32 m0, vcc_lo
	v_mfma_f32_16x16x32_bf16 v[96:99], v[144:147], v[228:231], v[96:99]
	ds_read_b128 v[124:127], v12 offset:6144
	global_load_lds_dwordx4 v0, s[98:99]
	s_add_u32 m0, m0, 0x2000
	v_mfma_f32_16x16x32_bf16 v[92:95], v[148:151], v[160:163], v[92:95]
	ds_read_b128 v[128:131], v13
	global_load_lds_dwordx4 v1, s[98:99]
	s_add_u32 m0, m0, 0x2000
	v_mfma_f32_16x16x32_bf16 v[88:91], v[148:151], v[164:167], v[88:91]
	ds_read_b128 v[132:135], v13 offset:2048
	global_load_lds_dwordx4 v2, s[98:99]
	s_add_u32 m0, m0, 0x2000
	v_mfma_f32_16x16x32_bf16 v[84:87], v[148:151], v[224:227], v[84:87]
	ds_read_b128 v[136:139], v13 offset:4096
	global_load_lds_dwordx4 v3, s[98:99]
	s_add_u32 m0, vcc_lo, 0x8000
	v_mfma_f32_16x16x32_bf16 v[80:83], v[148:151], v[228:231], v[80:83]
	ds_read_b128 v[140:143], v13 offset:6144
	global_load_lds_dwordx4 v4, s[100:101]
	s_add_u32 m0, m0, 0x2000
	v_mfma_f32_16x16x32_bf16 v[76:79], v[152:155], v[160:163], v[76:79]
	global_load_lds_dwordx4 v5, s[100:101]
	v_mfma_f32_16x16x32_bf16 v[72:75], v[152:155], v[164:167], v[72:75]
	s_add_u32 s98, s98, 0x80
	s_addc_u32 s99, s99, 0
	s_add_u32 s100, s100, 0x80
	s_addc_u32 s101, s101, 0
	v_mfma_f32_16x16x32_bf16 v[68:71], v[152:155], v[224:227], v[68:71]
	v_mfma_f32_16x16x32_bf16 v[64:67], v[152:155], v[228:231], v[64:67]
	v_mfma_f32_16x16x32_bf16 v[60:63], v[156:159], v[160:163], v[60:63]
	v_mfma_f32_16x16x32_bf16 v[56:59], v[156:159], v[164:167], v[56:59]
	v_mfma_f32_16x16x32_bf16 v[52:55], v[156:159], v[224:227], v[52:55]
	v_mfma_f32_16x16x32_bf16 v[48:51], v[156:159], v[228:231], v[48:51]
	s_waitcnt lgkmcnt(0)
	v_mfma_f32_16x16x32_bf16 v[108:111], v[112:115], v[128:131], v[108:111]
	ds_read_b128 v[144:147], v14
	v_mfma_f32_16x16x32_bf16 v[104:107], v[112:115], v[132:135], v[104:107]
	ds_read_b128 v[148:151], v14 offset:2048
	v_mfma_f32_16x16x32_bf16 v[100:103], v[112:115], v[136:139], v[100:103]
	ds_read_b128 v[152:155], v14 offset:4096
	v_mfma_f32_16x16x32_bf16 v[96:99], v[112:115], v[140:143], v[96:99]
	ds_read_b128 v[156:159], v14 offset:6144
	v_mfma_f32_16x16x32_bf16 v[92:95], v[116:119], v[128:131], v[92:95]
	ds_read_b128 v[160:163], v15
	v_mfma_f32_16x16x32_bf16 v[88:91], v[116:119], v[132:135], v[88:91]
	ds_read_b128 v[164:167], v15 offset:2048
	v_mfma_f32_16x16x32_bf16 v[84:87], v[116:119], v[136:139], v[84:87]
	ds_read_b128 v[224:227], v15 offset:4096
	v_mfma_f32_16x16x32_bf16 v[80:83], v[116:119], v[140:143], v[80:83]
	ds_read_b128 v[228:231], v15 offset:6144
	v_mfma_f32_16x16x32_bf16 v[76:79], v[120:123], v[128:131], v[76:79]
	v_mfma_f32_16x16x32_bf16 v[72:75], v[120:123], v[132:135], v[72:75]
	v_mfma_f32_16x16x32_bf16 v[68:71], v[120:123], v[136:139], v[68:71]
	v_mfma_f32_16x16x32_bf16 v[64:67], v[120:123], v[140:143], v[64:67]
	v_mfma_f32_16x16x32_bf16 v[60:63], v[124:127], v[128:131], v[60:63]
	v_mfma_f32_16x16x32_bf16 v[56:59], v[124:127], v[132:135], v[56:59]
	v_mfma_f32_16x16x32_bf16 v[52:55], v[124:127], v[136:139], v[52:55]
	v_mfma_f32_16x16x32_bf16 v[48:51], v[124:127], v[140:143], v[48:51]
	s_mov_b32 s5, s4
	s_add_u32 s4, s4, 0xc000
	s_sub_u32 vcc_lo, s4, 0x24000
	s_cselect_b32 s4, s4, vcc_lo
	s_add_i32 s19, s19, 1
	s_cmp_lt_u32 s19, 62
	s_cbranch_scc1 .Lmyg_steady
	s_andn2_b64 vcc, exec, s[8:9]
	s_cbranch_vccnz .Lmyg_prelast_n
	v_readlane_b32 s98, v250, 0
	v_readlane_b32 s99, v250, 1
	v_readlane_b32 s100, v250, 2
	v_readlane_b32 s101, v250, 3
	v_add_u32_e32 v12, s4, v214
	v_add_u32_e32 v13, s4, v10
	v_add_u32_e32 v14, s4, v216
	v_add_u32_e32 v15, s4, v11
	v_readfirstlane_b32 vcc_lo, v6
	s_nop 0
	s_add_u32 vcc_lo, vcc_lo, s5
	s_waitcnt vmcnt(6) lgkmcnt(0)
	s_barrier
	v_mfma_f32_16x16x32_bf16 v[108:111], v[144:147], v[160:163], v[108:111]
	ds_read_b128 v[112:115], v12
	v_mfma_f32_16x16x32_bf16 v[104:107], v[144:147], v[164:167], v[104:107]
	ds_read_b128 v[116:119], v12 offset:2048
	v_mfma_f32_16x16x32_bf16 v[100:103], v[144:147], v[224:227], v[100:103]
	ds_read_b128 v[120:123], v12 offset:4096
	s_mov_b32 m0, vcc_lo
	v_mfma_f32_16x16x32_bf16 v[96:99], v[144:147], v[228:231], v[96:99]
	ds_read_b128 v[124:127], v12 offset:6144
	global_load_lds_dwordx4 v0, s[98:99]
	s_add_u32 m0, m0, 0x2000
	v_mfma_f32_16x16x32_bf16 v[92:95], v[148:151], v[160:163], v[92:95]
	ds_read_b128 v[128:131], v13
	global_load_lds_dwordx4 v1, s[98:99]
	s_add_u32 m0, m0, 0x2000
	v_mfma_f32_16x16x32_bf16 v[88:91], v[148:151], v[164:167], v[88:91]
	ds_read_b128 v[132:135], v13 offset:2048
	global_load_lds_dwordx4 v2, s[98:99]
	s_add_u32 m0, m0, 0x2000
	v_mfma_f32_16x16x32_bf16 v[84:87], v[148:151], v[224:227], v[84:87]
	ds_read_b128 v[136:139], v13 offset:4096
	global_load_lds_dwordx4 v3, s[98:99]
	s_add_u32 m0, vcc_lo, 0x8000
	v_mfma_f32_16x16x32_bf16 v[80:83], v[148:151], v[228:231], v[80:83]
	ds_read_b128 v[140:143], v13 offset:6144
	global_load_lds_dwordx4 v4, s[100:101]
	s_add_u32 m0, m0, 0x2000
	v_mfma_f32_16x16x32_bf16 v[76:79], v[152:155], v[160:163], v[76:79]
	global_load_lds_dwordx4 v5, s[100:101]
	v_mfma_f32_16x16x32_bf16 v[72:75], v[152:155], v[164:167], v[72:75]
	s_add_u32 s98, s98, 0x80
	s_addc_u32 s99, s99, 0
	s_add_u32 s100, s100, 0x80
	s_addc_u32 s101, s101, 0
	v_mfma_f32_16x16x32_bf16 v[68:71], v[152:155], v[224:227], v[68:71]
	v_mfma_f32_16x16x32_bf16 v[64:67], v[152:155], v[228:231], v[64:67]
	v_mfma_f32_16x16x32_bf16 v[60:63], v[156:159], v[160:163], v[60:63]
	v_mfma_f32_16x16x32_bf16 v[56:59], v[156:159], v[164:167], v[56:59]
	v_mfma_f32_16x16x32_bf16 v[52:55], v[156:159], v[224:227], v[52:55]
	v_mfma_f32_16x16x32_bf16 v[48:51], v[156:159], v[228:231], v[48:51]
	s_waitcnt lgkmcnt(0)
	v_mfma_f32_16x16x32_bf16 v[108:111], v[112:115], v[128:131], v[108:111]
	ds_read_b128 v[144:147], v14
	v_mfma_f32_16x16x32_bf16 v[104:107], v[112:115], v[132:135], v[104:107]
	ds_read_b128 v[148:151], v14 offset:2048
	v_mfma_f32_16x16x32_bf16 v[100:103], v[112:115], v[136:139], v[100:103]
	ds_read_b128 v[152:155], v14 offset:4096
	v_mfma_f32_16x16x32_bf16 v[96:99], v[112:115], v[140:143], v[96:99]
	ds_read_b128 v[156:159], v14 offset:6144
	v_mfma_f32_16x16x32_bf16 v[92:95], v[116:119], v[128:131], v[92:95]
	ds_read_b128 v[160:163], v15
	v_mfma_f32_16x16x32_bf16 v[88:91], v[116:119], v[132:135], v[88:91]
	ds_read_b128 v[164:167], v15 offset:2048
	v_mfma_f32_16x16x32_bf16 v[84:87], v[116:119], v[136:139], v[84:87]
	ds_read_b128 v[224:227], v15 offset:4096
	v_mfma_f32_16x16x32_bf16 v[80:83], v[116:119], v[140:143], v[80:83]
	ds_read_b128 v[228:231], v15 offset:6144
	v_mfma_f32_16x16x32_bf16 v[76:79], v[120:123], v[128:131], v[76:79]
	v_mfma_f32_16x16x32_bf16 v[72:75], v[120:123], v[132:135], v[72:75]
	v_mfma_f32_16x16x32_bf16 v[68:71], v[120:123], v[136:139], v[68:71]
	v_mfma_f32_16x16x32_bf16 v[64:67], v[120:123], v[140:143], v[64:67]
	v_mfma_f32_16x16x32_bf16 v[60:63], v[124:127], v[128:131], v[60:63]
	v_mfma_f32_16x16x32_bf16 v[56:59], v[124:127], v[132:135], v[56:59]
	v_mfma_f32_16x16x32_bf16 v[52:55], v[124:127], v[136:139], v[52:55]
	v_mfma_f32_16x16x32_bf16 v[48:51], v[124:127], v[140:143], v[48:51]
	s_mov_b32 s5, s4
	s_add_u32 s4, s4, 0xc000
	s_sub_u32 vcc_lo, s4, 0x24000
	s_cselect_b32 s4, s4, vcc_lo
	v_add_u32_e32 v12, s4, v214
	v_add_u32_e32 v13, s4, v10
	v_add_u32_e32 v14, s4, v216
	v_add_u32_e32 v15, s4, v11
	v_readfirstlane_b32 vcc_lo, v6
	s_nop 0
	s_add_u32 vcc_lo, vcc_lo, s5
	s_waitcnt vmcnt(6) lgkmcnt(0)
	s_barrier
	v_mfma_f32_16x16x32_bf16 v[108:111], v[144:147], v[160:163], v[108:111]
	ds_read_b128 v[112:115], v12
	v_mfma_f32_16x16x32_bf16 v[104:107], v[144:147], v[164:167], v[104:107]
	ds_read_b128 v[116:119], v12 offset:2048
	v_mfma_f32_16x16x32_bf16 v[100:103], v[144:147], v[224:227], v[100:103]
	ds_read_b128 v[120:123], v12 offset:4096
	s_mov_b32 m0, vcc_lo
	v_mfma_f32_16x16x32_bf16 v[96:99], v[144:147], v[228:231], v[96:99]
	ds_read_b128 v[124:127], v12 offset:6144
	global_load_lds_dwordx4 v0, s[98:99]
	s_add_u32 m0, m0, 0x2000
	v_mfma_f32_16x16x32_bf16 v[92:95], v[148:151], v[160:163], v[92:95]
	ds_read_b128 v[128:131], v13
	global_load_lds_dwordx4 v1, s[98:99]
	s_add_u32 m0, m0, 0x2000
	v_mfma_f32_16x16x32_bf16 v[88:91], v[148:151], v[164:167], v[88:91]
	ds_read_b128 v[132:135], v13 offset:2048
	global_load_lds_dwordx4 v2, s[98:99]
	s_add_u32 m0, m0, 0x2000
	v_mfma_f32_16x16x32_bf16 v[84:87], v[148:151], v[224:227], v[84:87]
	ds_read_b128 v[136:139], v13 offset:4096
	global_load_lds_dwordx4 v3, s[98:99]
	s_add_u32 m0, vcc_lo, 0x8000
	v_mfma_f32_16x16x32_bf16 v[80:83], v[148:151], v[228:231], v[80:83]
	ds_read_b128 v[140:143], v13 offset:6144
	global_load_lds_dwordx4 v4, s[100:101]
	s_add_u32 m0, m0, 0x2000
	v_mfma_f32_16x16x32_bf16 v[76:79], v[152:155], v[160:163], v[76:79]
	global_load_lds_dwordx4 v5, s[100:101]
	v_mfma_f32_16x16x32_bf16 v[72:75], v[152:155], v[164:167], v[72:75]
	s_add_u32 s98, s98, 0x80
	s_addc_u32 s99, s99, 0
	s_add_u32 s100, s100, 0x80
	s_addc_u32 s101, s101, 0
	v_mfma_f32_16x16x32_bf16 v[68:71], v[152:155], v[224:227], v[68:71]
	v_mfma_f32_16x16x32_bf16 v[64:67], v[152:155], v[228:231], v[64:67]
	v_mfma_f32_16x16x32_bf16 v[60:63], v[156:159], v[160:163], v[60:63]
	v_mfma_f32_16x16x32_bf16 v[56:59], v[156:159], v[164:167], v[56:59]
	v_mfma_f32_16x16x32_bf16 v[52:55], v[156:159], v[224:227], v[52:55]
	v_mfma_f32_16x16x32_bf16 v[48:51], v[156:159], v[228:231], v[48:51]
	s_waitcnt lgkmcnt(0)
	v_mfma_f32_16x16x32_bf16 v[108:111], v[112:115], v[128:131], v[108:111]
	ds_read_b128 v[144:147], v14
	v_mfma_f32_16x16x32_bf16 v[104:107], v[112:115], v[132:135], v[104:107]
	ds_read_b128 v[148:151], v14 offset:2048
	v_mfma_f32_16x16x32_bf16 v[100:103], v[112:115], v[136:139], v[100:103]
	ds_read_b128 v[152:155], v14 offset:4096
	v_mfma_f32_16x16x32_bf16 v[96:99], v[112:115], v[140:143], v[96:99]
	ds_read_b128 v[156:159], v14 offset:6144
	v_mfma_f32_16x16x32_bf16 v[92:95], v[116:119], v[128:131], v[92:95]
	ds_read_b128 v[160:163], v15
	v_mfma_f32_16x16x32_bf16 v[88:91], v[116:119], v[132:135], v[88:91]
	ds_read_b128 v[164:167], v15 offset:2048
	v_mfma_f32_16x16x32_bf16 v[84:87], v[116:119], v[136:139], v[84:87]
	ds_read_b128 v[224:227], v15 offset:4096
	v_mfma_f32_16x16x32_bf16 v[80:83], v[116:119], v[140:143], v[80:83]
	ds_read_b128 v[228:231], v15 offset:6144
	v_mfma_f32_16x16x32_bf16 v[76:79], v[120:123], v[128:131], v[76:79]
	v_mfma_f32_16x16x32_bf16 v[72:75], v[120:123], v[132:135], v[72:75]
	v_mfma_f32_16x16x32_bf16 v[68:71], v[120:123], v[136:139], v[68:71]
	v_mfma_f32_16x16x32_bf16 v[64:67], v[120:123], v[140:143], v[64:67]
	v_mfma_f32_16x16x32_bf16 v[60:63], v[124:127], v[128:131], v[60:63]
	v_mfma_f32_16x16x32_bf16 v[56:59], v[124:127], v[132:135], v[56:59]
	v_mfma_f32_16x16x32_bf16 v[52:55], v[124:127], v[136:139], v[52:55]
	v_mfma_f32_16x16x32_bf16 v[48:51], v[124:127], v[140:143], v[48:51]
	s_mov_b32 s5, s4
	s_add_u32 s4, s4, 0xc000
	s_sub_u32 vcc_lo, s4, 0x24000
	s_cselect_b32 s4, s4, vcc_lo
	s_waitcnt lgkmcnt(0)
	v_mfma_f32_16x16x32_bf16 v[108:111], v[144:147], v[160:163], v[108:111]
	v_mfma_f32_16x16x32_bf16 v[104:107], v[144:147], v[164:167], v[104:107]
	v_mfma_f32_16x16x32_bf16 v[100:103], v[144:147], v[224:227], v[100:103]
	v_mfma_f32_16x16x32_bf16 v[96:99], v[144:147], v[228:231], v[96:99]
	v_mfma_f32_16x16x32_bf16 v[92:95], v[148:151], v[160:163], v[92:95]
	v_mfma_f32_16x16x32_bf16 v[88:91], v[148:151], v[164:167], v[88:91]
	v_mfma_f32_16x16x32_bf16 v[84:87], v[148:151], v[224:227], v[84:87]
	v_mfma_f32_16x16x32_bf16 v[80:83], v[148:151], v[228:231], v[80:83]
	v_mfma_f32_16x16x32_bf16 v[76:79], v[152:155], v[160:163], v[76:79]
	v_mfma_f32_16x16x32_bf16 v[72:75], v[152:155], v[164:167], v[72:75]
	v_mfma_f32_16x16x32_bf16 v[68:71], v[152:155], v[224:227], v[68:71]
	v_mfma_f32_16x16x32_bf16 v[64:67], v[152:155], v[228:231], v[64:67]
	v_mfma_f32_16x16x32_bf16 v[60:63], v[156:159], v[160:163], v[60:63]
	v_mfma_f32_16x16x32_bf16 v[56:59], v[156:159], v[164:167], v[56:59]
	v_mfma_f32_16x16x32_bf16 v[52:55], v[156:159], v[224:227], v[52:55]
	v_mfma_f32_16x16x32_bf16 v[48:51], v[156:159], v[228:231], v[48:51]
	s_and_b64 vcc, exec, s[10:11]
	s_nop 7
	s_branch .LBB0_1559
.Lmyg_prelast_n:
	v_add_u32_e32 v12, s4, v214
	v_add_u32_e32 v13, s4, v10
	v_add_u32_e32 v14, s4, v216
	v_add_u32_e32 v15, s4, v11
	s_waitcnt vmcnt(6) lgkmcnt(0)
	s_barrier
	v_mfma_f32_16x16x32_bf16 v[108:111], v[144:147], v[160:163], v[108:111]
	ds_read_b128 v[112:115], v12
	v_mfma_f32_16x16x32_bf16 v[104:107], v[144:147], v[164:167], v[104:107]
	ds_read_b128 v[116:119], v12 offset:2048
	v_mfma_f32_16x16x32_bf16 v[100:103], v[144:147], v[224:227], v[100:103]
	ds_read_b128 v[120:123], v12 offset:4096
	v_mfma_f32_16x16x32_bf16 v[96:99], v[144:147], v[228:231], v[96:99]
	ds_read_b128 v[124:127], v12 offset:6144
	v_mfma_f32_16x16x32_bf16 v[92:95], v[148:151], v[160:163], v[92:95]
	ds_read_b128 v[128:131], v13
	v_mfma_f32_16x16x32_bf16 v[88:91], v[148:151], v[164:167], v[88:91]
	ds_read_b128 v[132:135], v13 offset:2048
	v_mfma_f32_16x16x32_bf16 v[84:87], v[148:151], v[224:227], v[84:87]
	ds_read_b128 v[136:139], v13 offset:4096
	v_mfma_f32_16x16x32_bf16 v[80:83], v[148:151], v[228:231], v[80:83]
	ds_read_b128 v[140:143], v13 offset:6144
	v_mfma_f32_16x16x32_bf16 v[76:79], v[152:155], v[160:163], v[76:79]
	v_mfma_f32_16x16x32_bf16 v[72:75], v[152:155], v[164:167], v[72:75]
	v_mfma_f32_16x16x32_bf16 v[68:71], v[152:155], v[224:227], v[68:71]
	v_mfma_f32_16x16x32_bf16 v[64:67], v[152:155], v[228:231], v[64:67]
	v_mfma_f32_16x16x32_bf16 v[60:63], v[156:159], v[160:163], v[60:63]
	v_mfma_f32_16x16x32_bf16 v[56:59], v[156:159], v[164:167], v[56:59]
	v_mfma_f32_16x16x32_bf16 v[52:55], v[156:159], v[224:227], v[52:55]
	v_mfma_f32_16x16x32_bf16 v[48:51], v[156:159], v[228:231], v[48:51]
	s_waitcnt lgkmcnt(0)
	v_mfma_f32_16x16x32_bf16 v[108:111], v[112:115], v[128:131], v[108:111]
	ds_read_b128 v[144:147], v14
	v_mfma_f32_16x16x32_bf16 v[104:107], v[112:115], v[132:135], v[104:107]
	ds_read_b128 v[148:151], v14 offset:2048
	v_mfma_f32_16x16x32_bf16 v[100:103], v[112:115], v[136:139], v[100:103]
	ds_read_b128 v[152:155], v14 offset:4096
	v_mfma_f32_16x16x32_bf16 v[96:99], v[112:115], v[140:143], v[96:99]
	ds_read_b128 v[156:159], v14 offset:6144
	v_mfma_f32_16x16x32_bf16 v[92:95], v[116:119], v[128:131], v[92:95]
	ds_read_b128 v[160:163], v15
	v_mfma_f32_16x16x32_bf16 v[88:91], v[116:119], v[132:135], v[88:91]
	ds_read_b128 v[164:167], v15 offset:2048
	v_mfma_f32_16x16x32_bf16 v[84:87], v[116:119], v[136:139], v[84:87]
	ds_read_b128 v[224:227], v15 offset:4096
	v_mfma_f32_16x16x32_bf16 v[80:83], v[116:119], v[140:143], v[80:83]
	ds_read_b128 v[228:231], v15 offset:6144
	v_mfma_f32_16x16x32_bf16 v[76:79], v[120:123], v[128:131], v[76:79]
	v_mfma_f32_16x16x32_bf16 v[72:75], v[120:123], v[132:135], v[72:75]
	v_mfma_f32_16x16x32_bf16 v[68:71], v[120:123], v[136:139], v[68:71]
	v_mfma_f32_16x16x32_bf16 v[64:67], v[120:123], v[140:143], v[64:67]
	v_mfma_f32_16x16x32_bf16 v[60:63], v[124:127], v[128:131], v[60:63]
	v_mfma_f32_16x16x32_bf16 v[56:59], v[124:127], v[132:135], v[56:59]
	v_mfma_f32_16x16x32_bf16 v[52:55], v[124:127], v[136:139], v[52:55]
	v_mfma_f32_16x16x32_bf16 v[48:51], v[124:127], v[140:143], v[48:51]
	s_mov_b32 s5, s4
	s_add_u32 s4, s4, 0xc000
	s_sub_u32 vcc_lo, s4, 0x24000
	s_cselect_b32 s4, s4, vcc_lo
	v_add_u32_e32 v12, s4, v214
	v_add_u32_e32 v13, s4, v10
	v_add_u32_e32 v14, s4, v216
	v_add_u32_e32 v15, s4, v11
	s_waitcnt vmcnt(0) lgkmcnt(0)
	s_barrier
	v_mfma_f32_16x16x32_bf16 v[108:111], v[144:147], v[160:163], v[108:111]
	ds_read_b128 v[112:115], v12
	v_mfma_f32_16x16x32_bf16 v[104:107], v[144:147], v[164:167], v[104:107]
	ds_read_b128 v[116:119], v12 offset:2048
	v_mfma_f32_16x16x32_bf16 v[100:103], v[144:147], v[224:227], v[100:103]
	ds_read_b128 v[120:123], v12 offset:4096
	v_mfma_f32_16x16x32_bf16 v[96:99], v[144:147], v[228:231], v[96:99]
	ds_read_b128 v[124:127], v12 offset:6144
	v_mfma_f32_16x16x32_bf16 v[92:95], v[148:151], v[160:163], v[92:95]
	ds_read_b128 v[128:131], v13
	v_mfma_f32_16x16x32_bf16 v[88:91], v[148:151], v[164:167], v[88:91]
	ds_read_b128 v[132:135], v13 offset:2048
	v_mfma_f32_16x16x32_bf16 v[84:87], v[148:151], v[224:227], v[84:87]
	ds_read_b128 v[136:139], v13 offset:4096
	v_mfma_f32_16x16x32_bf16 v[80:83], v[148:151], v[228:231], v[80:83]
	ds_read_b128 v[140:143], v13 offset:6144
	v_mfma_f32_16x16x32_bf16 v[76:79], v[152:155], v[160:163], v[76:79]
	v_mfma_f32_16x16x32_bf16 v[72:75], v[152:155], v[164:167], v[72:75]
	v_mfma_f32_16x16x32_bf16 v[68:71], v[152:155], v[224:227], v[68:71]
	v_mfma_f32_16x16x32_bf16 v[64:67], v[152:155], v[228:231], v[64:67]
	v_mfma_f32_16x16x32_bf16 v[60:63], v[156:159], v[160:163], v[60:63]
	v_mfma_f32_16x16x32_bf16 v[56:59], v[156:159], v[164:167], v[56:59]
	v_mfma_f32_16x16x32_bf16 v[52:55], v[156:159], v[224:227], v[52:55]
	v_mfma_f32_16x16x32_bf16 v[48:51], v[156:159], v[228:231], v[48:51]
	s_waitcnt lgkmcnt(0)
	v_mfma_f32_16x16x32_bf16 v[108:111], v[112:115], v[128:131], v[108:111]
	ds_read_b128 v[144:147], v14
	v_mfma_f32_16x16x32_bf16 v[104:107], v[112:115], v[132:135], v[104:107]
	ds_read_b128 v[148:151], v14 offset:2048
	v_mfma_f32_16x16x32_bf16 v[100:103], v[112:115], v[136:139], v[100:103]
	ds_read_b128 v[152:155], v14 offset:4096
	v_mfma_f32_16x16x32_bf16 v[96:99], v[112:115], v[140:143], v[96:99]
	ds_read_b128 v[156:159], v14 offset:6144
	v_mfma_f32_16x16x32_bf16 v[92:95], v[116:119], v[128:131], v[92:95]
	ds_read_b128 v[160:163], v15
	v_mfma_f32_16x16x32_bf16 v[88:91], v[116:119], v[132:135], v[88:91]
	ds_read_b128 v[164:167], v15 offset:2048
	v_mfma_f32_16x16x32_bf16 v[84:87], v[116:119], v[136:139], v[84:87]
	ds_read_b128 v[224:227], v15 offset:4096
	v_mfma_f32_16x16x32_bf16 v[80:83], v[116:119], v[140:143], v[80:83]
	ds_read_b128 v[228:231], v15 offset:6144
	v_mfma_f32_16x16x32_bf16 v[76:79], v[120:123], v[128:131], v[76:79]
	v_mfma_f32_16x16x32_bf16 v[72:75], v[120:123], v[132:135], v[72:75]
	v_mfma_f32_16x16x32_bf16 v[68:71], v[120:123], v[136:139], v[68:71]
	v_mfma_f32_16x16x32_bf16 v[64:67], v[120:123], v[140:143], v[64:67]
	v_mfma_f32_16x16x32_bf16 v[60:63], v[124:127], v[128:131], v[60:63]
	v_mfma_f32_16x16x32_bf16 v[56:59], v[124:127], v[132:135], v[56:59]
	v_mfma_f32_16x16x32_bf16 v[52:55], v[124:127], v[136:139], v[52:55]
	v_mfma_f32_16x16x32_bf16 v[48:51], v[124:127], v[140:143], v[48:51]
	s_mov_b32 s5, s4
	s_add_u32 s4, s4, 0xc000
	s_sub_u32 vcc_lo, s4, 0x24000
	s_cselect_b32 s4, s4, vcc_lo
	s_waitcnt lgkmcnt(0)
	v_mfma_f32_16x16x32_bf16 v[108:111], v[144:147], v[160:163], v[108:111]
	v_mfma_f32_16x16x32_bf16 v[104:107], v[144:147], v[164:167], v[104:107]
	v_mfma_f32_16x16x32_bf16 v[100:103], v[144:147], v[224:227], v[100:103]
	v_mfma_f32_16x16x32_bf16 v[96:99], v[144:147], v[228:231], v[96:99]
	v_mfma_f32_16x16x32_bf16 v[92:95], v[148:151], v[160:163], v[92:95]
	v_mfma_f32_16x16x32_bf16 v[88:91], v[148:151], v[164:167], v[88:91]
	v_mfma_f32_16x16x32_bf16 v[84:87], v[148:151], v[224:227], v[84:87]
	v_mfma_f32_16x16x32_bf16 v[80:83], v[148:151], v[228:231], v[80:83]
	v_mfma_f32_16x16x32_bf16 v[76:79], v[152:155], v[160:163], v[76:79]
	v_mfma_f32_16x16x32_bf16 v[72:75], v[152:155], v[164:167], v[72:75]
	v_mfma_f32_16x16x32_bf16 v[68:71], v[152:155], v[224:227], v[68:71]
	v_mfma_f32_16x16x32_bf16 v[64:67], v[152:155], v[228:231], v[64:67]
	v_mfma_f32_16x16x32_bf16 v[60:63], v[156:159], v[160:163], v[60:63]
	v_mfma_f32_16x16x32_bf16 v[56:59], v[156:159], v[164:167], v[56:59]
	v_mfma_f32_16x16x32_bf16 v[52:55], v[156:159], v[224:227], v[52:55]
	v_mfma_f32_16x16x32_bf16 v[48:51], v[156:159], v[228:231], v[48:51]
	s_and_b64 vcc, exec, s[10:11]
	s_nop 7
	s_branch .LBB0_1559
